# shared hand-written EpiMerge epilogue (gate loads 16 blocks ahead, macc loads 8 ahead, counted vmcnt) replacing six serialized compiler epilogues
# speedup vs baseline: 1.0657x; 1.0192x over previous
.LBB0_829:
	s_lshr_b32 s98, s94, 2
	s_add_i32 s98, s98, 64
	s_and_b32 s99, s94, 3
	v_writelane_b32 v214, s98, 0
	v_writelane_b32 v214, s99, 1
	s_movk_i32 s98, 0x0
	v_writelane_b32 v214, s98, 2
	s_branch .Lepi_merge
.Lepi_ret_0:
	s_andn2_b64 vcc, exec, s[28:29]
	s_mov_b64 s[28:29], -1
	s_cbranch_vccnz .LBB0_822
	s_andn2_b64 vcc, exec, s[16:17]
	s_cbranch_vccnz .LBB0_821
	s_barrier
	s_branch .LBB0_821

.LBB0_845:
	s_lshr_b32 s98, s94, 2
	s_add_i32 s98, s98, 64
	s_and_b32 s99, s94, 3
	v_writelane_b32 v214, s98, 0
	v_writelane_b32 v214, s99, 1
	s_movk_i32 s98, 0x11
	v_writelane_b32 v214, s98, 2
	s_branch .Lepi_merge

.LBB0_861:
	s_lshr_b32 s98, s94, 2
	s_add_i32 s98, s98, 64
	s_and_b32 s99, s94, 3
	v_writelane_b32 v214, s98, 0
	v_writelane_b32 v214, s99, 1
	s_movk_i32 s98, 0x22
	v_writelane_b32 v214, s98, 2
	s_branch .Lepi_merge
.Lepi_ret_2:
	s_andn2_b64 vcc, exec, s[22:23]
	s_mov_b64 s[22:23], -1
	s_cbranch_vccnz .LBB0_854
	s_andn2_b64 vcc, exec, s[8:9]
	s_cbranch_vccnz .LBB0_853
	s_barrier
	s_branch .LBB0_853
.Lepi_merge:
	s_load_dwordx2 s[98:99], s[0:1], 0xd8
	s_load_dwordx2 s[100:101], s[0:1], 0xe0
	v_lshrrev_b32_e32 v196, 8, v156
	v_and_b32_e32 v197, 15, v156
	v_lshl_or_b32 v196, v196, 6, v197
	v_bfe_u32 v197, v156, 6, 2
	v_bfe_u32 v198, v156, 4, 2
	v_lshlrev_b32_e32 v198, 2, v198
	v_lshl_or_b32 v197, v197, 5, v198
	v_readlane_b32 vcc_lo, v214, 0
	v_readlane_b32 vcc_hi, v214, 1
	s_nop 1
	s_lshl_b32 vcc_lo, vcc_lo, 8
	s_lshl_b32 vcc_hi, vcc_hi, 8
	v_add_u32_e32 v196, vcc_lo, v196
	v_add_u32_e32 v197, vcc_hi, v197
	v_readlane_b32 vcc_hi, v214, 2
	s_and_b32 vcc_hi, vcc_hi, 15
	s_waitcnt lgkmcnt(0)
	s_add_u32 s100, s100, 0x2032400
	s_addc_u32 s101, s101, 0
	s_lshl_b32 vcc_lo, vcc_hi, 11
	s_add_u32 s100, s100, vcc_lo
	s_addc_u32 s101, s101, 0
	v_mov_b32_e32 v198, 0x3c00
	v_mul_hi_u32 v201, v196, v198
	v_mul_lo_u32 v200, v196, v198
	v_lshlrev_b32_e32 v199, 1, v197
	v_mov_b32_e32 v198, 0
	v_add_co_u32_e32 v200, vcc, v200, v199
	v_addc_co_u32_e32 v201, vcc, 0, v201, vcc
	v_lshl_add_u64 v[200:201], v[200:201], 0, s[100:101]
	v_lshlrev_b32_e32 v199, 2, v197
	v_lshrrev_b32_e32 v203, 20, v196
	v_lshlrev_b32_e32 v202, 12, v196
	v_add_co_u32_e32 v202, vcc, v202, v199
	v_addc_co_u32_e32 v203, vcc, 0, v203, vcc
	v_lshl_add_u64 v[202:203], v[202:203], 0, s[98:99]
	v_mov_b32_e32 v204, v202
	v_mov_b32_e32 v205, v203
	v_readlane_b32 vcc_hi, v214, 2
	s_and_b32 vcc_hi, vcc_hi, 15
	s_cmp_eq_u32 vcc_hi, 2
	s_cbranch_scc0 .Lepi_p1
	s_load_dwordx2 s[98:99], s[0:1], 0xe0
	v_readlane_b32 vcc_lo, v214, 0
	s_waitcnt lgkmcnt(0)
	s_add_u32 s100, s98, 0x13034000
	s_addc_u32 s101, s99, 0
	s_add_u32 s98, s98, 0x117b0000
	s_addc_u32 s99, s99, 0
	s_cmp_ge_u32 vcc_lo, 64
	s_cselect_b32 s98, s100, s98
	s_cselect_b32 s99, s101, s99
	v_lshlrev_b32_e32 v199, 1, v197
	v_lshrrev_b32_e32 v205, 21, v196
	v_lshlrev_b32_e32 v204, 11, v196
	v_add_co_u32_e32 v204, vcc, v204, v199
	v_addc_co_u32_e32 v205, vcc, 0, v205, vcc
	v_lshl_add_u64 v[204:205], v[204:205], 0, s[98:99]
.Lepi_p1:
	v_readlane_b32 vcc_hi, v214, 2
	s_and_b32 vcc_hi, vcc_hi, 15
	s_cmp_eq_u32 vcc_hi, 0
	s_cbranch_scc0 .Lepi_p1_nost
	global_load_dwordx2 v[164:165], v[200:201], off
	global_load_dwordx2 v[166:167], v[200:201], off offset:32
	global_load_dwordx2 v[168:169], v[200:201], off offset:256
	global_load_dwordx2 v[170:171], v[200:201], off offset:288
	s_mov_b64 s[100:101], 0x3c000
	v_lshl_add_u64 v[200:201], v[200:201], 0, s[100:101]
	global_load_dwordx2 v[172:173], v[200:201], off
	global_load_dwordx2 v[174:175], v[200:201], off offset:32
	global_load_dwordx2 v[176:177], v[200:201], off offset:256
	global_load_dwordx2 v[178:179], v[200:201], off offset:288
	s_mov_b64 s[100:101], 0x3c000
	v_lshl_add_u64 v[200:201], v[200:201], 0, s[100:101]
	global_load_dwordx2 v[180:181], v[200:201], off
	global_load_dwordx2 v[182:183], v[200:201], off offset:32
	global_load_dwordx2 v[184:185], v[200:201], off offset:256
	global_load_dwordx2 v[186:187], v[200:201], off offset:288
	s_mov_b64 s[100:101], 0x3c000
	v_lshl_add_u64 v[200:201], v[200:201], 0, s[100:101]
	global_load_dwordx2 v[188:189], v[200:201], off
	global_load_dwordx2 v[190:191], v[200:201], off offset:32
	global_load_dwordx2 v[192:193], v[200:201], off offset:256
	global_load_dwordx2 v[194:195], v[200:201], off offset:288
	s_waitcnt vmcnt(15)
	v_lshlrev_b32_e32 v206, 16, v164
	v_and_b32_e32 v207, 0xffff0000, v164
	v_lshlrev_b32_e32 v208, 16, v165
	v_and_b32_e32 v209, 0xffff0000, v165
	v_mul_f32_e32 v206, 0xbfb8aa3b, v206
	v_mul_f32_e32 v207, 0xbfb8aa3b, v207
	v_mul_f32_e32 v208, 0xbfb8aa3b, v208
	v_mul_f32_e32 v209, 0xbfb8aa3b, v209
	v_exp_f32_e32 v206, v206
	v_exp_f32_e32 v207, v207
	v_exp_f32_e32 v208, v208
	v_exp_f32_e32 v209, v209
	s_nop 0
	v_add_f32_e32 v206, 1.0, v206
	v_add_f32_e32 v207, 1.0, v207
	v_add_f32_e32 v208, 1.0, v208
	v_add_f32_e32 v209, 1.0, v209
	v_rcp_f32_e32 v206, v206
	v_rcp_f32_e32 v207, v207
	v_rcp_f32_e32 v208, v208
	v_rcp_f32_e32 v209, v209
	s_nop 0
	v_pk_mul_f32 v[124:125], v[124:125], v[206:207]
	v_pk_mul_f32 v[126:127], v[126:127], v[208:209]
	global_store_dwordx4 v[204:205], v[124:127], off
	s_mov_b64 s[100:101], 0x12c000
	v_lshl_add_u64 v[200:201], v[200:201], 0, s[100:101]
	global_load_dwordx2 v[164:165], v[200:201], off
	s_waitcnt vmcnt(16)
	v_lshlrev_b32_e32 v206, 16, v166
	v_and_b32_e32 v207, 0xffff0000, v166
	v_lshlrev_b32_e32 v208, 16, v167
	v_and_b32_e32 v209, 0xffff0000, v167
	v_mul_f32_e32 v206, 0xbfb8aa3b, v206
	v_mul_f32_e32 v207, 0xbfb8aa3b, v207
	v_mul_f32_e32 v208, 0xbfb8aa3b, v208
	v_mul_f32_e32 v209, 0xbfb8aa3b, v209
	v_exp_f32_e32 v206, v206
	v_exp_f32_e32 v207, v207
	v_exp_f32_e32 v208, v208
	v_exp_f32_e32 v209, v209
	s_nop 0
	v_add_f32_e32 v206, 1.0, v206
	v_add_f32_e32 v207, 1.0, v207
	v_add_f32_e32 v208, 1.0, v208
	v_add_f32_e32 v209, 1.0, v209
	v_rcp_f32_e32 v206, v206
	v_rcp_f32_e32 v207, v207
	v_rcp_f32_e32 v208, v208
	v_rcp_f32_e32 v209, v209
	s_nop 0
	v_pk_mul_f32 v[120:121], v[120:121], v[206:207]
	v_pk_mul_f32 v[122:123], v[122:123], v[208:209]
	global_store_dwordx4 v[204:205], v[120:123], off offset:64
	global_load_dwordx2 v[166:167], v[200:201], off offset:32
	s_waitcnt vmcnt(17)
	v_lshlrev_b32_e32 v206, 16, v168
	v_and_b32_e32 v207, 0xffff0000, v168
	v_lshlrev_b32_e32 v208, 16, v169
	v_and_b32_e32 v209, 0xffff0000, v169
	v_mul_f32_e32 v206, 0xbfb8aa3b, v206
	v_mul_f32_e32 v207, 0xbfb8aa3b, v207
	v_mul_f32_e32 v208, 0xbfb8aa3b, v208
	v_mul_f32_e32 v209, 0xbfb8aa3b, v209
	v_exp_f32_e32 v206, v206
	v_exp_f32_e32 v207, v207
	v_exp_f32_e32 v208, v208
	v_exp_f32_e32 v209, v209
	s_nop 0
	v_add_f32_e32 v206, 1.0, v206
	v_add_f32_e32 v207, 1.0, v207
	v_add_f32_e32 v208, 1.0, v208
	v_add_f32_e32 v209, 1.0, v209
	v_rcp_f32_e32 v206, v206
	v_rcp_f32_e32 v207, v207
	v_rcp_f32_e32 v208, v208
	v_rcp_f32_e32 v209, v209
	s_nop 0
	v_pk_mul_f32 v[116:117], v[116:117], v[206:207]
	v_pk_mul_f32 v[118:119], v[118:119], v[208:209]
	global_store_dwordx4 v[204:205], v[116:119], off offset:512
	global_load_dwordx2 v[168:169], v[200:201], off offset:256
	s_waitcnt vmcnt(18)
	v_lshlrev_b32_e32 v206, 16, v170
	v_and_b32_e32 v207, 0xffff0000, v170
	v_lshlrev_b32_e32 v208, 16, v171
	v_and_b32_e32 v209, 0xffff0000, v171
	v_mul_f32_e32 v206, 0xbfb8aa3b, v206
	v_mul_f32_e32 v207, 0xbfb8aa3b, v207
	v_mul_f32_e32 v208, 0xbfb8aa3b, v208
	v_mul_f32_e32 v209, 0xbfb8aa3b, v209
	v_exp_f32_e32 v206, v206
	v_exp_f32_e32 v207, v207
	v_exp_f32_e32 v208, v208
	v_exp_f32_e32 v209, v209
	s_nop 0
	v_add_f32_e32 v206, 1.0, v206
	v_add_f32_e32 v207, 1.0, v207
	v_add_f32_e32 v208, 1.0, v208
	v_add_f32_e32 v209, 1.0, v209
	v_rcp_f32_e32 v206, v206
	v_rcp_f32_e32 v207, v207
	v_rcp_f32_e32 v208, v208
	v_rcp_f32_e32 v209, v209
	s_nop 0
	v_pk_mul_f32 v[112:113], v[112:113], v[206:207]
	v_pk_mul_f32 v[114:115], v[114:115], v[208:209]
	global_store_dwordx4 v[204:205], v[112:115], off offset:576
	global_load_dwordx2 v[170:171], v[200:201], off offset:288
	s_waitcnt vmcnt(19)
	v_lshlrev_b32_e32 v206, 16, v172
	v_and_b32_e32 v207, 0xffff0000, v172
	v_lshlrev_b32_e32 v208, 16, v173
	v_and_b32_e32 v209, 0xffff0000, v173
	v_mul_f32_e32 v206, 0xbfb8aa3b, v206
	v_mul_f32_e32 v207, 0xbfb8aa3b, v207
	v_mul_f32_e32 v208, 0xbfb8aa3b, v208
	v_mul_f32_e32 v209, 0xbfb8aa3b, v209
	v_exp_f32_e32 v206, v206
	v_exp_f32_e32 v207, v207
	v_exp_f32_e32 v208, v208
	v_exp_f32_e32 v209, v209
	s_nop 0
	v_add_f32_e32 v206, 1.0, v206
	v_add_f32_e32 v207, 1.0, v207
	v_add_f32_e32 v208, 1.0, v208
	v_add_f32_e32 v209, 1.0, v209
	v_rcp_f32_e32 v206, v206
	v_rcp_f32_e32 v207, v207
	v_rcp_f32_e32 v208, v208
	v_rcp_f32_e32 v209, v209
	s_nop 0
	v_pk_mul_f32 v[108:109], v[108:109], v[206:207]
	v_pk_mul_f32 v[110:111], v[110:111], v[208:209]
	s_mov_b64 s[100:101], 0x10000
	v_lshl_add_u64 v[204:205], v[204:205], 0, s[100:101]
	global_store_dwordx4 v[204:205], v[108:111], off
	s_mov_b64 s[100:101], 0x3c000
	v_lshl_add_u64 v[200:201], v[200:201], 0, s[100:101]
	global_load_dwordx2 v[172:173], v[200:201], off
	s_waitcnt vmcnt(20)
	v_lshlrev_b32_e32 v206, 16, v174
	v_and_b32_e32 v207, 0xffff0000, v174
	v_lshlrev_b32_e32 v208, 16, v175
	v_and_b32_e32 v209, 0xffff0000, v175
	v_mul_f32_e32 v206, 0xbfb8aa3b, v206
	v_mul_f32_e32 v207, 0xbfb8aa3b, v207
	v_mul_f32_e32 v208, 0xbfb8aa3b, v208
	v_mul_f32_e32 v209, 0xbfb8aa3b, v209
	v_exp_f32_e32 v206, v206
	v_exp_f32_e32 v207, v207
	v_exp_f32_e32 v208, v208
	v_exp_f32_e32 v209, v209
	s_nop 0
	v_add_f32_e32 v206, 1.0, v206
	v_add_f32_e32 v207, 1.0, v207
	v_add_f32_e32 v208, 1.0, v208
	v_add_f32_e32 v209, 1.0, v209
	v_rcp_f32_e32 v206, v206
	v_rcp_f32_e32 v207, v207
	v_rcp_f32_e32 v208, v208
	v_rcp_f32_e32 v209, v209
	s_nop 0
	v_pk_mul_f32 v[104:105], v[104:105], v[206:207]
	v_pk_mul_f32 v[106:107], v[106:107], v[208:209]
	global_store_dwordx4 v[204:205], v[104:107], off offset:64
	global_load_dwordx2 v[174:175], v[200:201], off offset:32
	s_waitcnt vmcnt(21)
	v_lshlrev_b32_e32 v206, 16, v176
	v_and_b32_e32 v207, 0xffff0000, v176
	v_lshlrev_b32_e32 v208, 16, v177
	v_and_b32_e32 v209, 0xffff0000, v177
	v_mul_f32_e32 v206, 0xbfb8aa3b, v206
	v_mul_f32_e32 v207, 0xbfb8aa3b, v207
	v_mul_f32_e32 v208, 0xbfb8aa3b, v208
	v_mul_f32_e32 v209, 0xbfb8aa3b, v209
	v_exp_f32_e32 v206, v206
	v_exp_f32_e32 v207, v207
	v_exp_f32_e32 v208, v208
	v_exp_f32_e32 v209, v209
	s_nop 0
	v_add_f32_e32 v206, 1.0, v206
	v_add_f32_e32 v207, 1.0, v207
	v_add_f32_e32 v208, 1.0, v208
	v_add_f32_e32 v209, 1.0, v209
	v_rcp_f32_e32 v206, v206
	v_rcp_f32_e32 v207, v207
	v_rcp_f32_e32 v208, v208
	v_rcp_f32_e32 v209, v209
	s_nop 0
	v_pk_mul_f32 v[100:101], v[100:101], v[206:207]
	v_pk_mul_f32 v[102:103], v[102:103], v[208:209]
	global_store_dwordx4 v[204:205], v[100:103], off offset:512
	global_load_dwordx2 v[176:177], v[200:201], off offset:256
	s_waitcnt vmcnt(22)
	v_lshlrev_b32_e32 v206, 16, v178
	v_and_b32_e32 v207, 0xffff0000, v178
	v_lshlrev_b32_e32 v208, 16, v179
	v_and_b32_e32 v209, 0xffff0000, v179
	v_mul_f32_e32 v206, 0xbfb8aa3b, v206
	v_mul_f32_e32 v207, 0xbfb8aa3b, v207
	v_mul_f32_e32 v208, 0xbfb8aa3b, v208
	v_mul_f32_e32 v209, 0xbfb8aa3b, v209
	v_exp_f32_e32 v206, v206
	v_exp_f32_e32 v207, v207
	v_exp_f32_e32 v208, v208
	v_exp_f32_e32 v209, v209
	s_nop 0
	v_add_f32_e32 v206, 1.0, v206
	v_add_f32_e32 v207, 1.0, v207
	v_add_f32_e32 v208, 1.0, v208
	v_add_f32_e32 v209, 1.0, v209
	v_rcp_f32_e32 v206, v206
	v_rcp_f32_e32 v207, v207
	v_rcp_f32_e32 v208, v208
	v_rcp_f32_e32 v209, v209
	s_nop 0
	v_pk_mul_f32 v[96:97], v[96:97], v[206:207]
	v_pk_mul_f32 v[98:99], v[98:99], v[208:209]
	global_store_dwordx4 v[204:205], v[96:99], off offset:576
	global_load_dwordx2 v[178:179], v[200:201], off offset:288
	s_waitcnt vmcnt(23)
	v_lshlrev_b32_e32 v206, 16, v180
	v_and_b32_e32 v207, 0xffff0000, v180
	v_lshlrev_b32_e32 v208, 16, v181
	v_and_b32_e32 v209, 0xffff0000, v181
	v_mul_f32_e32 v206, 0xbfb8aa3b, v206
	v_mul_f32_e32 v207, 0xbfb8aa3b, v207
	v_mul_f32_e32 v208, 0xbfb8aa3b, v208
	v_mul_f32_e32 v209, 0xbfb8aa3b, v209
	v_exp_f32_e32 v206, v206
	v_exp_f32_e32 v207, v207
	v_exp_f32_e32 v208, v208
	v_exp_f32_e32 v209, v209
	s_nop 0
	v_add_f32_e32 v206, 1.0, v206
	v_add_f32_e32 v207, 1.0, v207
	v_add_f32_e32 v208, 1.0, v208
	v_add_f32_e32 v209, 1.0, v209
	v_rcp_f32_e32 v206, v206
	v_rcp_f32_e32 v207, v207
	v_rcp_f32_e32 v208, v208
	v_rcp_f32_e32 v209, v209
	s_nop 0
	v_pk_mul_f32 v[92:93], v[92:93], v[206:207]
	v_pk_mul_f32 v[94:95], v[94:95], v[208:209]
	s_mov_b64 s[100:101], 0x10000
	v_lshl_add_u64 v[204:205], v[204:205], 0, s[100:101]
	global_store_dwordx4 v[204:205], v[92:95], off
	s_mov_b64 s[100:101], 0x3c000
	v_lshl_add_u64 v[200:201], v[200:201], 0, s[100:101]
	global_load_dwordx2 v[180:181], v[200:201], off
	s_waitcnt vmcnt(24)
	v_lshlrev_b32_e32 v206, 16, v182
	v_and_b32_e32 v207, 0xffff0000, v182
	v_lshlrev_b32_e32 v208, 16, v183
	v_and_b32_e32 v209, 0xffff0000, v183
	v_mul_f32_e32 v206, 0xbfb8aa3b, v206
	v_mul_f32_e32 v207, 0xbfb8aa3b, v207
	v_mul_f32_e32 v208, 0xbfb8aa3b, v208
	v_mul_f32_e32 v209, 0xbfb8aa3b, v209
	v_exp_f32_e32 v206, v206
	v_exp_f32_e32 v207, v207
	v_exp_f32_e32 v208, v208
	v_exp_f32_e32 v209, v209
	s_nop 0
	v_add_f32_e32 v206, 1.0, v206
	v_add_f32_e32 v207, 1.0, v207
	v_add_f32_e32 v208, 1.0, v208
	v_add_f32_e32 v209, 1.0, v209
	v_rcp_f32_e32 v206, v206
	v_rcp_f32_e32 v207, v207
	v_rcp_f32_e32 v208, v208
	v_rcp_f32_e32 v209, v209
	s_nop 0
	v_pk_mul_f32 v[88:89], v[88:89], v[206:207]
	v_pk_mul_f32 v[90:91], v[90:91], v[208:209]
	global_store_dwordx4 v[204:205], v[88:91], off offset:64
	global_load_dwordx2 v[182:183], v[200:201], off offset:32
	s_waitcnt vmcnt(25)
	v_lshlrev_b32_e32 v206, 16, v184
	v_and_b32_e32 v207, 0xffff0000, v184
	v_lshlrev_b32_e32 v208, 16, v185
	v_and_b32_e32 v209, 0xffff0000, v185
	v_mul_f32_e32 v206, 0xbfb8aa3b, v206
	v_mul_f32_e32 v207, 0xbfb8aa3b, v207
	v_mul_f32_e32 v208, 0xbfb8aa3b, v208
	v_mul_f32_e32 v209, 0xbfb8aa3b, v209
	v_exp_f32_e32 v206, v206
	v_exp_f32_e32 v207, v207
	v_exp_f32_e32 v208, v208
	v_exp_f32_e32 v209, v209
	s_nop 0
	v_add_f32_e32 v206, 1.0, v206
	v_add_f32_e32 v207, 1.0, v207
	v_add_f32_e32 v208, 1.0, v208
	v_add_f32_e32 v209, 1.0, v209
	v_rcp_f32_e32 v206, v206
	v_rcp_f32_e32 v207, v207
	v_rcp_f32_e32 v208, v208
	v_rcp_f32_e32 v209, v209
	s_nop 0
	v_pk_mul_f32 v[84:85], v[84:85], v[206:207]
	v_pk_mul_f32 v[86:87], v[86:87], v[208:209]
	global_store_dwordx4 v[204:205], v[84:87], off offset:512
	global_load_dwordx2 v[184:185], v[200:201], off offset:256
	s_waitcnt vmcnt(26)
	v_lshlrev_b32_e32 v206, 16, v186
	v_and_b32_e32 v207, 0xffff0000, v186
	v_lshlrev_b32_e32 v208, 16, v187
	v_and_b32_e32 v209, 0xffff0000, v187
	v_mul_f32_e32 v206, 0xbfb8aa3b, v206
	v_mul_f32_e32 v207, 0xbfb8aa3b, v207
	v_mul_f32_e32 v208, 0xbfb8aa3b, v208
	v_mul_f32_e32 v209, 0xbfb8aa3b, v209
	v_exp_f32_e32 v206, v206
	v_exp_f32_e32 v207, v207
	v_exp_f32_e32 v208, v208
	v_exp_f32_e32 v209, v209
	s_nop 0
	v_add_f32_e32 v206, 1.0, v206
	v_add_f32_e32 v207, 1.0, v207
	v_add_f32_e32 v208, 1.0, v208
	v_add_f32_e32 v209, 1.0, v209
	v_rcp_f32_e32 v206, v206
	v_rcp_f32_e32 v207, v207
	v_rcp_f32_e32 v208, v208
	v_rcp_f32_e32 v209, v209
	s_nop 0
	v_pk_mul_f32 v[80:81], v[80:81], v[206:207]
	v_pk_mul_f32 v[82:83], v[82:83], v[208:209]
	global_store_dwordx4 v[204:205], v[80:83], off offset:576
	global_load_dwordx2 v[186:187], v[200:201], off offset:288
	s_waitcnt vmcnt(27)
	v_lshlrev_b32_e32 v206, 16, v188
	v_and_b32_e32 v207, 0xffff0000, v188
	v_lshlrev_b32_e32 v208, 16, v189
	v_and_b32_e32 v209, 0xffff0000, v189
	v_mul_f32_e32 v206, 0xbfb8aa3b, v206
	v_mul_f32_e32 v207, 0xbfb8aa3b, v207
	v_mul_f32_e32 v208, 0xbfb8aa3b, v208
	v_mul_f32_e32 v209, 0xbfb8aa3b, v209
	v_exp_f32_e32 v206, v206
	v_exp_f32_e32 v207, v207
	v_exp_f32_e32 v208, v208
	v_exp_f32_e32 v209, v209
	s_nop 0
	v_add_f32_e32 v206, 1.0, v206
	v_add_f32_e32 v207, 1.0, v207
	v_add_f32_e32 v208, 1.0, v208
	v_add_f32_e32 v209, 1.0, v209
	v_rcp_f32_e32 v206, v206
	v_rcp_f32_e32 v207, v207
	v_rcp_f32_e32 v208, v208
	v_rcp_f32_e32 v209, v209
	s_nop 0
	v_pk_mul_f32 v[76:77], v[76:77], v[206:207]
	v_pk_mul_f32 v[78:79], v[78:79], v[208:209]
	s_mov_b64 s[100:101], 0x10000
	v_lshl_add_u64 v[204:205], v[204:205], 0, s[100:101]
	global_store_dwordx4 v[204:205], v[76:79], off
	s_mov_b64 s[100:101], 0x3c000
	v_lshl_add_u64 v[200:201], v[200:201], 0, s[100:101]
	global_load_dwordx2 v[188:189], v[200:201], off
	s_waitcnt vmcnt(28)
	v_lshlrev_b32_e32 v206, 16, v190
	v_and_b32_e32 v207, 0xffff0000, v190
	v_lshlrev_b32_e32 v208, 16, v191
	v_and_b32_e32 v209, 0xffff0000, v191
	v_mul_f32_e32 v206, 0xbfb8aa3b, v206
	v_mul_f32_e32 v207, 0xbfb8aa3b, v207
	v_mul_f32_e32 v208, 0xbfb8aa3b, v208
	v_mul_f32_e32 v209, 0xbfb8aa3b, v209
	v_exp_f32_e32 v206, v206
	v_exp_f32_e32 v207, v207
	v_exp_f32_e32 v208, v208
	v_exp_f32_e32 v209, v209
	s_nop 0
	v_add_f32_e32 v206, 1.0, v206
	v_add_f32_e32 v207, 1.0, v207
	v_add_f32_e32 v208, 1.0, v208
	v_add_f32_e32 v209, 1.0, v209
	v_rcp_f32_e32 v206, v206
	v_rcp_f32_e32 v207, v207
	v_rcp_f32_e32 v208, v208
	v_rcp_f32_e32 v209, v209
	s_nop 0
	v_pk_mul_f32 v[72:73], v[72:73], v[206:207]
	v_pk_mul_f32 v[74:75], v[74:75], v[208:209]
	global_store_dwordx4 v[204:205], v[72:75], off offset:64
	global_load_dwordx2 v[190:191], v[200:201], off offset:32
	s_waitcnt vmcnt(29)
	v_lshlrev_b32_e32 v206, 16, v192
	v_and_b32_e32 v207, 0xffff0000, v192
	v_lshlrev_b32_e32 v208, 16, v193
	v_and_b32_e32 v209, 0xffff0000, v193
	v_mul_f32_e32 v206, 0xbfb8aa3b, v206
	v_mul_f32_e32 v207, 0xbfb8aa3b, v207
	v_mul_f32_e32 v208, 0xbfb8aa3b, v208
	v_mul_f32_e32 v209, 0xbfb8aa3b, v209
	v_exp_f32_e32 v206, v206
	v_exp_f32_e32 v207, v207
	v_exp_f32_e32 v208, v208
	v_exp_f32_e32 v209, v209
	s_nop 0
	v_add_f32_e32 v206, 1.0, v206
	v_add_f32_e32 v207, 1.0, v207
	v_add_f32_e32 v208, 1.0, v208
	v_add_f32_e32 v209, 1.0, v209
	v_rcp_f32_e32 v206, v206
	v_rcp_f32_e32 v207, v207
	v_rcp_f32_e32 v208, v208
	v_rcp_f32_e32 v209, v209
	s_nop 0
	v_pk_mul_f32 v[68:69], v[68:69], v[206:207]
	v_pk_mul_f32 v[70:71], v[70:71], v[208:209]
	global_store_dwordx4 v[204:205], v[68:71], off offset:512
	global_load_dwordx2 v[192:193], v[200:201], off offset:256
	s_waitcnt vmcnt(30)
	v_lshlrev_b32_e32 v206, 16, v194
	v_and_b32_e32 v207, 0xffff0000, v194
	v_lshlrev_b32_e32 v208, 16, v195
	v_and_b32_e32 v209, 0xffff0000, v195
	v_mul_f32_e32 v206, 0xbfb8aa3b, v206
	v_mul_f32_e32 v207, 0xbfb8aa3b, v207
	v_mul_f32_e32 v208, 0xbfb8aa3b, v208
	v_mul_f32_e32 v209, 0xbfb8aa3b, v209
	v_exp_f32_e32 v206, v206
	v_exp_f32_e32 v207, v207
	v_exp_f32_e32 v208, v208
	v_exp_f32_e32 v209, v209
	s_nop 0
	v_add_f32_e32 v206, 1.0, v206
	v_add_f32_e32 v207, 1.0, v207
	v_add_f32_e32 v208, 1.0, v208
	v_add_f32_e32 v209, 1.0, v209
	v_rcp_f32_e32 v206, v206
	v_rcp_f32_e32 v207, v207
	v_rcp_f32_e32 v208, v208
	v_rcp_f32_e32 v209, v209
	s_nop 0
	v_pk_mul_f32 v[64:65], v[64:65], v[206:207]
	v_pk_mul_f32 v[66:67], v[66:67], v[208:209]
	global_store_dwordx4 v[204:205], v[64:67], off offset:576
	global_load_dwordx2 v[194:195], v[200:201], off offset:288
	s_waitcnt vmcnt(30)
	v_lshlrev_b32_e32 v206, 16, v164
	v_and_b32_e32 v207, 0xffff0000, v164
	v_lshlrev_b32_e32 v208, 16, v165
	v_and_b32_e32 v209, 0xffff0000, v165
	v_mul_f32_e32 v206, 0xbfb8aa3b, v206
	v_mul_f32_e32 v207, 0xbfb8aa3b, v207
	v_mul_f32_e32 v208, 0xbfb8aa3b, v208
	v_mul_f32_e32 v209, 0xbfb8aa3b, v209
	v_exp_f32_e32 v206, v206
	v_exp_f32_e32 v207, v207
	v_exp_f32_e32 v208, v208
	v_exp_f32_e32 v209, v209
	s_nop 0
	v_add_f32_e32 v206, 1.0, v206
	v_add_f32_e32 v207, 1.0, v207
	v_add_f32_e32 v208, 1.0, v208
	v_add_f32_e32 v209, 1.0, v209
	v_rcp_f32_e32 v206, v206
	v_rcp_f32_e32 v207, v207
	v_rcp_f32_e32 v208, v208
	v_rcp_f32_e32 v209, v209
	s_nop 0
	v_pk_mul_f32 v[60:61], v[60:61], v[206:207]
	v_pk_mul_f32 v[62:63], v[62:63], v[208:209]
	s_mov_b64 s[100:101], 0x50000
	v_lshl_add_u64 v[204:205], v[204:205], 0, s[100:101]
	global_store_dwordx4 v[204:205], v[60:63], off
	s_waitcnt vmcnt(29)
	v_lshlrev_b32_e32 v206, 16, v166
	v_and_b32_e32 v207, 0xffff0000, v166
	v_lshlrev_b32_e32 v208, 16, v167
	v_and_b32_e32 v209, 0xffff0000, v167
	v_mul_f32_e32 v206, 0xbfb8aa3b, v206
	v_mul_f32_e32 v207, 0xbfb8aa3b, v207
	v_mul_f32_e32 v208, 0xbfb8aa3b, v208
	v_mul_f32_e32 v209, 0xbfb8aa3b, v209
	v_exp_f32_e32 v206, v206
	v_exp_f32_e32 v207, v207
	v_exp_f32_e32 v208, v208
	v_exp_f32_e32 v209, v209
	s_nop 0
	v_add_f32_e32 v206, 1.0, v206
	v_add_f32_e32 v207, 1.0, v207
	v_add_f32_e32 v208, 1.0, v208
	v_add_f32_e32 v209, 1.0, v209
	v_rcp_f32_e32 v206, v206
	v_rcp_f32_e32 v207, v207
	v_rcp_f32_e32 v208, v208
	v_rcp_f32_e32 v209, v209
	s_nop 0
	v_pk_mul_f32 v[56:57], v[56:57], v[206:207]
	v_pk_mul_f32 v[58:59], v[58:59], v[208:209]
	global_store_dwordx4 v[204:205], v[56:59], off offset:64
	s_waitcnt vmcnt(28)
	v_lshlrev_b32_e32 v206, 16, v168
	v_and_b32_e32 v207, 0xffff0000, v168
	v_lshlrev_b32_e32 v208, 16, v169
	v_and_b32_e32 v209, 0xffff0000, v169
	v_mul_f32_e32 v206, 0xbfb8aa3b, v206
	v_mul_f32_e32 v207, 0xbfb8aa3b, v207
	v_mul_f32_e32 v208, 0xbfb8aa3b, v208
	v_mul_f32_e32 v209, 0xbfb8aa3b, v209
	v_exp_f32_e32 v206, v206
	v_exp_f32_e32 v207, v207
	v_exp_f32_e32 v208, v208
	v_exp_f32_e32 v209, v209
	s_nop 0
	v_add_f32_e32 v206, 1.0, v206
	v_add_f32_e32 v207, 1.0, v207
	v_add_f32_e32 v208, 1.0, v208
	v_add_f32_e32 v209, 1.0, v209
	v_rcp_f32_e32 v206, v206
	v_rcp_f32_e32 v207, v207
	v_rcp_f32_e32 v208, v208
	v_rcp_f32_e32 v209, v209
	s_nop 0
	v_pk_mul_f32 v[52:53], v[52:53], v[206:207]
	v_pk_mul_f32 v[54:55], v[54:55], v[208:209]
	global_store_dwordx4 v[204:205], v[52:55], off offset:512
	s_waitcnt vmcnt(27)
	v_lshlrev_b32_e32 v206, 16, v170
	v_and_b32_e32 v207, 0xffff0000, v170
	v_lshlrev_b32_e32 v208, 16, v171
	v_and_b32_e32 v209, 0xffff0000, v171
	v_mul_f32_e32 v206, 0xbfb8aa3b, v206
	v_mul_f32_e32 v207, 0xbfb8aa3b, v207
	v_mul_f32_e32 v208, 0xbfb8aa3b, v208
	v_mul_f32_e32 v209, 0xbfb8aa3b, v209
	v_exp_f32_e32 v206, v206
	v_exp_f32_e32 v207, v207
	v_exp_f32_e32 v208, v208
	v_exp_f32_e32 v209, v209
	s_nop 0
	v_add_f32_e32 v206, 1.0, v206
	v_add_f32_e32 v207, 1.0, v207
	v_add_f32_e32 v208, 1.0, v208
	v_add_f32_e32 v209, 1.0, v209
	v_rcp_f32_e32 v206, v206
	v_rcp_f32_e32 v207, v207
	v_rcp_f32_e32 v208, v208
	v_rcp_f32_e32 v209, v209
	s_nop 0
	v_pk_mul_f32 v[48:49], v[48:49], v[206:207]
	v_pk_mul_f32 v[50:51], v[50:51], v[208:209]
	global_store_dwordx4 v[204:205], v[48:51], off offset:576
	s_waitcnt vmcnt(26)
	v_lshlrev_b32_e32 v206, 16, v172
	v_and_b32_e32 v207, 0xffff0000, v172
	v_lshlrev_b32_e32 v208, 16, v173
	v_and_b32_e32 v209, 0xffff0000, v173
	v_mul_f32_e32 v206, 0xbfb8aa3b, v206
	v_mul_f32_e32 v207, 0xbfb8aa3b, v207
	v_mul_f32_e32 v208, 0xbfb8aa3b, v208
	v_mul_f32_e32 v209, 0xbfb8aa3b, v209
	v_exp_f32_e32 v206, v206
	v_exp_f32_e32 v207, v207
	v_exp_f32_e32 v208, v208
	v_exp_f32_e32 v209, v209
	s_nop 0
	v_add_f32_e32 v206, 1.0, v206
	v_add_f32_e32 v207, 1.0, v207
	v_add_f32_e32 v208, 1.0, v208
	v_add_f32_e32 v209, 1.0, v209
	v_rcp_f32_e32 v206, v206
	v_rcp_f32_e32 v207, v207
	v_rcp_f32_e32 v208, v208
	v_rcp_f32_e32 v209, v209
	s_nop 0
	v_pk_mul_f32 v[44:45], v[44:45], v[206:207]
	v_pk_mul_f32 v[46:47], v[46:47], v[208:209]
	s_mov_b64 s[100:101], 0x10000
	v_lshl_add_u64 v[204:205], v[204:205], 0, s[100:101]
	global_store_dwordx4 v[204:205], v[44:47], off
	s_waitcnt vmcnt(25)
	v_lshlrev_b32_e32 v206, 16, v174
	v_and_b32_e32 v207, 0xffff0000, v174
	v_lshlrev_b32_e32 v208, 16, v175
	v_and_b32_e32 v209, 0xffff0000, v175
	v_mul_f32_e32 v206, 0xbfb8aa3b, v206
	v_mul_f32_e32 v207, 0xbfb8aa3b, v207
	v_mul_f32_e32 v208, 0xbfb8aa3b, v208
	v_mul_f32_e32 v209, 0xbfb8aa3b, v209
	v_exp_f32_e32 v206, v206
	v_exp_f32_e32 v207, v207
	v_exp_f32_e32 v208, v208
	v_exp_f32_e32 v209, v209
	s_nop 0
	v_add_f32_e32 v206, 1.0, v206
	v_add_f32_e32 v207, 1.0, v207
	v_add_f32_e32 v208, 1.0, v208
	v_add_f32_e32 v209, 1.0, v209
	v_rcp_f32_e32 v206, v206
	v_rcp_f32_e32 v207, v207
	v_rcp_f32_e32 v208, v208
	v_rcp_f32_e32 v209, v209
	s_nop 0
	v_pk_mul_f32 v[40:41], v[40:41], v[206:207]
	v_pk_mul_f32 v[42:43], v[42:43], v[208:209]
	global_store_dwordx4 v[204:205], v[40:43], off offset:64
	s_waitcnt vmcnt(24)
	v_lshlrev_b32_e32 v206, 16, v176
	v_and_b32_e32 v207, 0xffff0000, v176
	v_lshlrev_b32_e32 v208, 16, v177
	v_and_b32_e32 v209, 0xffff0000, v177
	v_mul_f32_e32 v206, 0xbfb8aa3b, v206
	v_mul_f32_e32 v207, 0xbfb8aa3b, v207
	v_mul_f32_e32 v208, 0xbfb8aa3b, v208
	v_mul_f32_e32 v209, 0xbfb8aa3b, v209
	v_exp_f32_e32 v206, v206
	v_exp_f32_e32 v207, v207
	v_exp_f32_e32 v208, v208
	v_exp_f32_e32 v209, v209
	s_nop 0
	v_add_f32_e32 v206, 1.0, v206
	v_add_f32_e32 v207, 1.0, v207
	v_add_f32_e32 v208, 1.0, v208
	v_add_f32_e32 v209, 1.0, v209
	v_rcp_f32_e32 v206, v206
	v_rcp_f32_e32 v207, v207
	v_rcp_f32_e32 v208, v208
	v_rcp_f32_e32 v209, v209
	s_nop 0
	v_pk_mul_f32 v[36:37], v[36:37], v[206:207]
	v_pk_mul_f32 v[38:39], v[38:39], v[208:209]
	global_store_dwordx4 v[204:205], v[36:39], off offset:512
	s_waitcnt vmcnt(23)
	v_lshlrev_b32_e32 v206, 16, v178
	v_and_b32_e32 v207, 0xffff0000, v178
	v_lshlrev_b32_e32 v208, 16, v179
	v_and_b32_e32 v209, 0xffff0000, v179
	v_mul_f32_e32 v206, 0xbfb8aa3b, v206
	v_mul_f32_e32 v207, 0xbfb8aa3b, v207
	v_mul_f32_e32 v208, 0xbfb8aa3b, v208
	v_mul_f32_e32 v209, 0xbfb8aa3b, v209
	v_exp_f32_e32 v206, v206
	v_exp_f32_e32 v207, v207
	v_exp_f32_e32 v208, v208
	v_exp_f32_e32 v209, v209
	s_nop 0
	v_add_f32_e32 v206, 1.0, v206
	v_add_f32_e32 v207, 1.0, v207
	v_add_f32_e32 v208, 1.0, v208
	v_add_f32_e32 v209, 1.0, v209
	v_rcp_f32_e32 v206, v206
	v_rcp_f32_e32 v207, v207
	v_rcp_f32_e32 v208, v208
	v_rcp_f32_e32 v209, v209
	s_nop 0
	v_pk_mul_f32 v[32:33], v[32:33], v[206:207]
	v_pk_mul_f32 v[34:35], v[34:35], v[208:209]
	global_store_dwordx4 v[204:205], v[32:35], off offset:576
	s_waitcnt vmcnt(22)
	v_lshlrev_b32_e32 v206, 16, v180
	v_and_b32_e32 v207, 0xffff0000, v180
	v_lshlrev_b32_e32 v208, 16, v181
	v_and_b32_e32 v209, 0xffff0000, v181
	v_mul_f32_e32 v206, 0xbfb8aa3b, v206
	v_mul_f32_e32 v207, 0xbfb8aa3b, v207
	v_mul_f32_e32 v208, 0xbfb8aa3b, v208
	v_mul_f32_e32 v209, 0xbfb8aa3b, v209
	v_exp_f32_e32 v206, v206
	v_exp_f32_e32 v207, v207
	v_exp_f32_e32 v208, v208
	v_exp_f32_e32 v209, v209
	s_nop 0
	v_add_f32_e32 v206, 1.0, v206
	v_add_f32_e32 v207, 1.0, v207
	v_add_f32_e32 v208, 1.0, v208
	v_add_f32_e32 v209, 1.0, v209
	v_rcp_f32_e32 v206, v206
	v_rcp_f32_e32 v207, v207
	v_rcp_f32_e32 v208, v208
	v_rcp_f32_e32 v209, v209
	s_nop 0
	v_pk_mul_f32 v[28:29], v[28:29], v[206:207]
	v_pk_mul_f32 v[30:31], v[30:31], v[208:209]
	s_mov_b64 s[100:101], 0x10000
	v_lshl_add_u64 v[204:205], v[204:205], 0, s[100:101]
	global_store_dwordx4 v[204:205], v[28:31], off
	s_waitcnt vmcnt(21)
	v_lshlrev_b32_e32 v206, 16, v182
	v_and_b32_e32 v207, 0xffff0000, v182
	v_lshlrev_b32_e32 v208, 16, v183
	v_and_b32_e32 v209, 0xffff0000, v183
	v_mul_f32_e32 v206, 0xbfb8aa3b, v206
	v_mul_f32_e32 v207, 0xbfb8aa3b, v207
	v_mul_f32_e32 v208, 0xbfb8aa3b, v208
	v_mul_f32_e32 v209, 0xbfb8aa3b, v209
	v_exp_f32_e32 v206, v206
	v_exp_f32_e32 v207, v207
	v_exp_f32_e32 v208, v208
	v_exp_f32_e32 v209, v209
	s_nop 0
	v_add_f32_e32 v206, 1.0, v206
	v_add_f32_e32 v207, 1.0, v207
	v_add_f32_e32 v208, 1.0, v208
	v_add_f32_e32 v209, 1.0, v209
	v_rcp_f32_e32 v206, v206
	v_rcp_f32_e32 v207, v207
	v_rcp_f32_e32 v208, v208
	v_rcp_f32_e32 v209, v209
	s_nop 0
	v_pk_mul_f32 v[24:25], v[24:25], v[206:207]
	v_pk_mul_f32 v[26:27], v[26:27], v[208:209]
	global_store_dwordx4 v[204:205], v[24:27], off offset:64
	s_waitcnt vmcnt(20)
	v_lshlrev_b32_e32 v206, 16, v184
	v_and_b32_e32 v207, 0xffff0000, v184
	v_lshlrev_b32_e32 v208, 16, v185
	v_and_b32_e32 v209, 0xffff0000, v185
	v_mul_f32_e32 v206, 0xbfb8aa3b, v206
	v_mul_f32_e32 v207, 0xbfb8aa3b, v207
	v_mul_f32_e32 v208, 0xbfb8aa3b, v208
	v_mul_f32_e32 v209, 0xbfb8aa3b, v209
	v_exp_f32_e32 v206, v206
	v_exp_f32_e32 v207, v207
	v_exp_f32_e32 v208, v208
	v_exp_f32_e32 v209, v209
	s_nop 0
	v_add_f32_e32 v206, 1.0, v206
	v_add_f32_e32 v207, 1.0, v207
	v_add_f32_e32 v208, 1.0, v208
	v_add_f32_e32 v209, 1.0, v209
	v_rcp_f32_e32 v206, v206
	v_rcp_f32_e32 v207, v207
	v_rcp_f32_e32 v208, v208
	v_rcp_f32_e32 v209, v209
	s_nop 0
	v_pk_mul_f32 v[20:21], v[20:21], v[206:207]
	v_pk_mul_f32 v[22:23], v[22:23], v[208:209]
	global_store_dwordx4 v[204:205], v[20:23], off offset:512
	s_waitcnt vmcnt(19)
	v_lshlrev_b32_e32 v206, 16, v186
	v_and_b32_e32 v207, 0xffff0000, v186
	v_lshlrev_b32_e32 v208, 16, v187
	v_and_b32_e32 v209, 0xffff0000, v187
	v_mul_f32_e32 v206, 0xbfb8aa3b, v206
	v_mul_f32_e32 v207, 0xbfb8aa3b, v207
	v_mul_f32_e32 v208, 0xbfb8aa3b, v208
	v_mul_f32_e32 v209, 0xbfb8aa3b, v209
	v_exp_f32_e32 v206, v206
	v_exp_f32_e32 v207, v207
	v_exp_f32_e32 v208, v208
	v_exp_f32_e32 v209, v209
	s_nop 0
	v_add_f32_e32 v206, 1.0, v206
	v_add_f32_e32 v207, 1.0, v207
	v_add_f32_e32 v208, 1.0, v208
	v_add_f32_e32 v209, 1.0, v209
	v_rcp_f32_e32 v206, v206
	v_rcp_f32_e32 v207, v207
	v_rcp_f32_e32 v208, v208
	v_rcp_f32_e32 v209, v209
	s_nop 0
	v_pk_mul_f32 v[16:17], v[16:17], v[206:207]
	v_pk_mul_f32 v[18:19], v[18:19], v[208:209]
	global_store_dwordx4 v[204:205], v[16:19], off offset:576
	s_waitcnt vmcnt(18)
	v_lshlrev_b32_e32 v206, 16, v188
	v_and_b32_e32 v207, 0xffff0000, v188
	v_lshlrev_b32_e32 v208, 16, v189
	v_and_b32_e32 v209, 0xffff0000, v189
	v_mul_f32_e32 v206, 0xbfb8aa3b, v206
	v_mul_f32_e32 v207, 0xbfb8aa3b, v207
	v_mul_f32_e32 v208, 0xbfb8aa3b, v208
	v_mul_f32_e32 v209, 0xbfb8aa3b, v209
	v_exp_f32_e32 v206, v206
	v_exp_f32_e32 v207, v207
	v_exp_f32_e32 v208, v208
	v_exp_f32_e32 v209, v209
	s_nop 0
	v_add_f32_e32 v206, 1.0, v206
	v_add_f32_e32 v207, 1.0, v207
	v_add_f32_e32 v208, 1.0, v208
	v_add_f32_e32 v209, 1.0, v209
	v_rcp_f32_e32 v206, v206
	v_rcp_f32_e32 v207, v207
	v_rcp_f32_e32 v208, v208
	v_rcp_f32_e32 v209, v209
	s_nop 0
	v_pk_mul_f32 v[12:13], v[12:13], v[206:207]
	v_pk_mul_f32 v[14:15], v[14:15], v[208:209]
	s_mov_b64 s[100:101], 0x10000
	v_lshl_add_u64 v[204:205], v[204:205], 0, s[100:101]
	global_store_dwordx4 v[204:205], v[12:15], off
	s_waitcnt vmcnt(17)
	v_lshlrev_b32_e32 v206, 16, v190
	v_and_b32_e32 v207, 0xffff0000, v190
	v_lshlrev_b32_e32 v208, 16, v191
	v_and_b32_e32 v209, 0xffff0000, v191
	v_mul_f32_e32 v206, 0xbfb8aa3b, v206
	v_mul_f32_e32 v207, 0xbfb8aa3b, v207
	v_mul_f32_e32 v208, 0xbfb8aa3b, v208
	v_mul_f32_e32 v209, 0xbfb8aa3b, v209
	v_exp_f32_e32 v206, v206
	v_exp_f32_e32 v207, v207
	v_exp_f32_e32 v208, v208
	v_exp_f32_e32 v209, v209
	s_nop 0
	v_add_f32_e32 v206, 1.0, v206
	v_add_f32_e32 v207, 1.0, v207
	v_add_f32_e32 v208, 1.0, v208
	v_add_f32_e32 v209, 1.0, v209
	v_rcp_f32_e32 v206, v206
	v_rcp_f32_e32 v207, v207
	v_rcp_f32_e32 v208, v208
	v_rcp_f32_e32 v209, v209
	s_nop 0
	v_pk_mul_f32 v[8:9], v[8:9], v[206:207]
	v_pk_mul_f32 v[10:11], v[10:11], v[208:209]
	global_store_dwordx4 v[204:205], v[8:11], off offset:64
	s_waitcnt vmcnt(16)
	v_lshlrev_b32_e32 v206, 16, v192
	v_and_b32_e32 v207, 0xffff0000, v192
	v_lshlrev_b32_e32 v208, 16, v193
	v_and_b32_e32 v209, 0xffff0000, v193
	v_mul_f32_e32 v206, 0xbfb8aa3b, v206
	v_mul_f32_e32 v207, 0xbfb8aa3b, v207
	v_mul_f32_e32 v208, 0xbfb8aa3b, v208
	v_mul_f32_e32 v209, 0xbfb8aa3b, v209
	v_exp_f32_e32 v206, v206
	v_exp_f32_e32 v207, v207
	v_exp_f32_e32 v208, v208
	v_exp_f32_e32 v209, v209
	s_nop 0
	v_add_f32_e32 v206, 1.0, v206
	v_add_f32_e32 v207, 1.0, v207
	v_add_f32_e32 v208, 1.0, v208
	v_add_f32_e32 v209, 1.0, v209
	v_rcp_f32_e32 v206, v206
	v_rcp_f32_e32 v207, v207
	v_rcp_f32_e32 v208, v208
	v_rcp_f32_e32 v209, v209
	s_nop 0
	v_pk_mul_f32 v[4:5], v[4:5], v[206:207]
	v_pk_mul_f32 v[6:7], v[6:7], v[208:209]
	global_store_dwordx4 v[204:205], v[4:7], off offset:512
	s_waitcnt vmcnt(15)
	v_lshlrev_b32_e32 v206, 16, v194
	v_and_b32_e32 v207, 0xffff0000, v194
	v_lshlrev_b32_e32 v208, 16, v195
	v_and_b32_e32 v209, 0xffff0000, v195
	v_mul_f32_e32 v206, 0xbfb8aa3b, v206
	v_mul_f32_e32 v207, 0xbfb8aa3b, v207
	v_mul_f32_e32 v208, 0xbfb8aa3b, v208
	v_mul_f32_e32 v209, 0xbfb8aa3b, v209
	v_exp_f32_e32 v206, v206
	v_exp_f32_e32 v207, v207
	v_exp_f32_e32 v208, v208
	v_exp_f32_e32 v209, v209
	s_nop 0
	v_add_f32_e32 v206, 1.0, v206
	v_add_f32_e32 v207, 1.0, v207
	v_add_f32_e32 v208, 1.0, v208
	v_add_f32_e32 v209, 1.0, v209
	v_rcp_f32_e32 v206, v206
	v_rcp_f32_e32 v207, v207
	v_rcp_f32_e32 v208, v208
	v_rcp_f32_e32 v209, v209
	s_nop 0
	v_pk_mul_f32 v[0:1], v[0:1], v[206:207]
	v_pk_mul_f32 v[2:3], v[2:3], v[208:209]
	global_store_dwordx4 v[204:205], v[0:3], off offset:576
	s_branch .Lepi_done
.Lepi_p1_nost:
	global_load_dwordx2 v[164:165], v[200:201], off
	global_load_dwordx2 v[166:167], v[200:201], off offset:32
	global_load_dwordx2 v[168:169], v[200:201], off offset:256
	global_load_dwordx2 v[170:171], v[200:201], off offset:288
	s_mov_b64 s[100:101], 0x3c000
	v_lshl_add_u64 v[200:201], v[200:201], 0, s[100:101]
	global_load_dwordx2 v[172:173], v[200:201], off
	global_load_dwordx2 v[174:175], v[200:201], off offset:32
	global_load_dwordx2 v[176:177], v[200:201], off offset:256
	global_load_dwordx2 v[178:179], v[200:201], off offset:288
	s_mov_b64 s[100:101], 0x3c000
	v_lshl_add_u64 v[200:201], v[200:201], 0, s[100:101]
	global_load_dwordx2 v[180:181], v[200:201], off
	global_load_dwordx2 v[182:183], v[200:201], off offset:32
	global_load_dwordx2 v[184:185], v[200:201], off offset:256
	global_load_dwordx2 v[186:187], v[200:201], off offset:288
	s_mov_b64 s[100:101], 0x3c000
	v_lshl_add_u64 v[200:201], v[200:201], 0, s[100:101]
	global_load_dwordx2 v[188:189], v[200:201], off
	global_load_dwordx2 v[190:191], v[200:201], off offset:32
	global_load_dwordx2 v[192:193], v[200:201], off offset:256
	global_load_dwordx2 v[194:195], v[200:201], off offset:288
	s_waitcnt vmcnt(15)
	v_lshlrev_b32_e32 v206, 16, v164
	v_and_b32_e32 v207, 0xffff0000, v164
	v_lshlrev_b32_e32 v208, 16, v165
	v_and_b32_e32 v209, 0xffff0000, v165
	v_mul_f32_e32 v206, 0xbfb8aa3b, v206
	v_mul_f32_e32 v207, 0xbfb8aa3b, v207
	v_mul_f32_e32 v208, 0xbfb8aa3b, v208
	v_mul_f32_e32 v209, 0xbfb8aa3b, v209
	v_exp_f32_e32 v206, v206
	v_exp_f32_e32 v207, v207
	v_exp_f32_e32 v208, v208
	v_exp_f32_e32 v209, v209
	s_nop 0
	v_add_f32_e32 v206, 1.0, v206
	v_add_f32_e32 v207, 1.0, v207
	v_add_f32_e32 v208, 1.0, v208
	v_add_f32_e32 v209, 1.0, v209
	v_rcp_f32_e32 v206, v206
	v_rcp_f32_e32 v207, v207
	v_rcp_f32_e32 v208, v208
	v_rcp_f32_e32 v209, v209
	s_nop 0
	v_pk_mul_f32 v[124:125], v[124:125], v[206:207]
	v_pk_mul_f32 v[126:127], v[126:127], v[208:209]
	s_mov_b64 s[100:101], 0x12c000
	v_lshl_add_u64 v[200:201], v[200:201], 0, s[100:101]
	global_load_dwordx2 v[164:165], v[200:201], off
	s_waitcnt vmcnt(15)
	v_lshlrev_b32_e32 v206, 16, v166
	v_and_b32_e32 v207, 0xffff0000, v166
	v_lshlrev_b32_e32 v208, 16, v167
	v_and_b32_e32 v209, 0xffff0000, v167
	v_mul_f32_e32 v206, 0xbfb8aa3b, v206
	v_mul_f32_e32 v207, 0xbfb8aa3b, v207
	v_mul_f32_e32 v208, 0xbfb8aa3b, v208
	v_mul_f32_e32 v209, 0xbfb8aa3b, v209
	v_exp_f32_e32 v206, v206
	v_exp_f32_e32 v207, v207
	v_exp_f32_e32 v208, v208
	v_exp_f32_e32 v209, v209
	s_nop 0
	v_add_f32_e32 v206, 1.0, v206
	v_add_f32_e32 v207, 1.0, v207
	v_add_f32_e32 v208, 1.0, v208
	v_add_f32_e32 v209, 1.0, v209
	v_rcp_f32_e32 v206, v206
	v_rcp_f32_e32 v207, v207
	v_rcp_f32_e32 v208, v208
	v_rcp_f32_e32 v209, v209
	s_nop 0
	v_pk_mul_f32 v[120:121], v[120:121], v[206:207]
	v_pk_mul_f32 v[122:123], v[122:123], v[208:209]
	global_load_dwordx2 v[166:167], v[200:201], off offset:32
	s_waitcnt vmcnt(15)
	v_lshlrev_b32_e32 v206, 16, v168
	v_and_b32_e32 v207, 0xffff0000, v168
	v_lshlrev_b32_e32 v208, 16, v169
	v_and_b32_e32 v209, 0xffff0000, v169
	v_mul_f32_e32 v206, 0xbfb8aa3b, v206
	v_mul_f32_e32 v207, 0xbfb8aa3b, v207
	v_mul_f32_e32 v208, 0xbfb8aa3b, v208
	v_mul_f32_e32 v209, 0xbfb8aa3b, v209
	v_exp_f32_e32 v206, v206
	v_exp_f32_e32 v207, v207
	v_exp_f32_e32 v208, v208
	v_exp_f32_e32 v209, v209
	s_nop 0
	v_add_f32_e32 v206, 1.0, v206
	v_add_f32_e32 v207, 1.0, v207
	v_add_f32_e32 v208, 1.0, v208
	v_add_f32_e32 v209, 1.0, v209
	v_rcp_f32_e32 v206, v206
	v_rcp_f32_e32 v207, v207
	v_rcp_f32_e32 v208, v208
	v_rcp_f32_e32 v209, v209
	s_nop 0
	v_pk_mul_f32 v[116:117], v[116:117], v[206:207]
	v_pk_mul_f32 v[118:119], v[118:119], v[208:209]
	global_load_dwordx2 v[168:169], v[200:201], off offset:256
	s_waitcnt vmcnt(15)
	v_lshlrev_b32_e32 v206, 16, v170
	v_and_b32_e32 v207, 0xffff0000, v170
	v_lshlrev_b32_e32 v208, 16, v171
	v_and_b32_e32 v209, 0xffff0000, v171
	v_mul_f32_e32 v206, 0xbfb8aa3b, v206
	v_mul_f32_e32 v207, 0xbfb8aa3b, v207
	v_mul_f32_e32 v208, 0xbfb8aa3b, v208
	v_mul_f32_e32 v209, 0xbfb8aa3b, v209
	v_exp_f32_e32 v206, v206
	v_exp_f32_e32 v207, v207
	v_exp_f32_e32 v208, v208
	v_exp_f32_e32 v209, v209
	s_nop 0
	v_add_f32_e32 v206, 1.0, v206
	v_add_f32_e32 v207, 1.0, v207
	v_add_f32_e32 v208, 1.0, v208
	v_add_f32_e32 v209, 1.0, v209
	v_rcp_f32_e32 v206, v206
	v_rcp_f32_e32 v207, v207
	v_rcp_f32_e32 v208, v208
	v_rcp_f32_e32 v209, v209
	s_nop 0
	v_pk_mul_f32 v[112:113], v[112:113], v[206:207]
	v_pk_mul_f32 v[114:115], v[114:115], v[208:209]
	global_load_dwordx2 v[170:171], v[200:201], off offset:288
	s_waitcnt vmcnt(15)
	v_lshlrev_b32_e32 v206, 16, v172
	v_and_b32_e32 v207, 0xffff0000, v172
	v_lshlrev_b32_e32 v208, 16, v173
	v_and_b32_e32 v209, 0xffff0000, v173
	v_mul_f32_e32 v206, 0xbfb8aa3b, v206
	v_mul_f32_e32 v207, 0xbfb8aa3b, v207
	v_mul_f32_e32 v208, 0xbfb8aa3b, v208
	v_mul_f32_e32 v209, 0xbfb8aa3b, v209
	v_exp_f32_e32 v206, v206
	v_exp_f32_e32 v207, v207
	v_exp_f32_e32 v208, v208
	v_exp_f32_e32 v209, v209
	s_nop 0
	v_add_f32_e32 v206, 1.0, v206
	v_add_f32_e32 v207, 1.0, v207
	v_add_f32_e32 v208, 1.0, v208
	v_add_f32_e32 v209, 1.0, v209
	v_rcp_f32_e32 v206, v206
	v_rcp_f32_e32 v207, v207
	v_rcp_f32_e32 v208, v208
	v_rcp_f32_e32 v209, v209
	s_nop 0
	v_pk_mul_f32 v[108:109], v[108:109], v[206:207]
	v_pk_mul_f32 v[110:111], v[110:111], v[208:209]
	s_mov_b64 s[100:101], 0x3c000
	v_lshl_add_u64 v[200:201], v[200:201], 0, s[100:101]
	global_load_dwordx2 v[172:173], v[200:201], off
	s_waitcnt vmcnt(15)
	v_lshlrev_b32_e32 v206, 16, v174
	v_and_b32_e32 v207, 0xffff0000, v174
	v_lshlrev_b32_e32 v208, 16, v175
	v_and_b32_e32 v209, 0xffff0000, v175
	v_mul_f32_e32 v206, 0xbfb8aa3b, v206
	v_mul_f32_e32 v207, 0xbfb8aa3b, v207
	v_mul_f32_e32 v208, 0xbfb8aa3b, v208
	v_mul_f32_e32 v209, 0xbfb8aa3b, v209
	v_exp_f32_e32 v206, v206
	v_exp_f32_e32 v207, v207
	v_exp_f32_e32 v208, v208
	v_exp_f32_e32 v209, v209
	s_nop 0
	v_add_f32_e32 v206, 1.0, v206
	v_add_f32_e32 v207, 1.0, v207
	v_add_f32_e32 v208, 1.0, v208
	v_add_f32_e32 v209, 1.0, v209
	v_rcp_f32_e32 v206, v206
	v_rcp_f32_e32 v207, v207
	v_rcp_f32_e32 v208, v208
	v_rcp_f32_e32 v209, v209
	s_nop 0
	v_pk_mul_f32 v[104:105], v[104:105], v[206:207]
	v_pk_mul_f32 v[106:107], v[106:107], v[208:209]
	global_load_dwordx2 v[174:175], v[200:201], off offset:32
	s_waitcnt vmcnt(15)
	v_lshlrev_b32_e32 v206, 16, v176
	v_and_b32_e32 v207, 0xffff0000, v176
	v_lshlrev_b32_e32 v208, 16, v177
	v_and_b32_e32 v209, 0xffff0000, v177
	v_mul_f32_e32 v206, 0xbfb8aa3b, v206
	v_mul_f32_e32 v207, 0xbfb8aa3b, v207
	v_mul_f32_e32 v208, 0xbfb8aa3b, v208
	v_mul_f32_e32 v209, 0xbfb8aa3b, v209
	v_exp_f32_e32 v206, v206
	v_exp_f32_e32 v207, v207
	v_exp_f32_e32 v208, v208
	v_exp_f32_e32 v209, v209
	s_nop 0
	v_add_f32_e32 v206, 1.0, v206
	v_add_f32_e32 v207, 1.0, v207
	v_add_f32_e32 v208, 1.0, v208
	v_add_f32_e32 v209, 1.0, v209
	v_rcp_f32_e32 v206, v206
	v_rcp_f32_e32 v207, v207
	v_rcp_f32_e32 v208, v208
	v_rcp_f32_e32 v209, v209
	s_nop 0
	v_pk_mul_f32 v[100:101], v[100:101], v[206:207]
	v_pk_mul_f32 v[102:103], v[102:103], v[208:209]
	global_load_dwordx2 v[176:177], v[200:201], off offset:256
	s_waitcnt vmcnt(15)
	v_lshlrev_b32_e32 v206, 16, v178
	v_and_b32_e32 v207, 0xffff0000, v178
	v_lshlrev_b32_e32 v208, 16, v179
	v_and_b32_e32 v209, 0xffff0000, v179
	v_mul_f32_e32 v206, 0xbfb8aa3b, v206
	v_mul_f32_e32 v207, 0xbfb8aa3b, v207
	v_mul_f32_e32 v208, 0xbfb8aa3b, v208
	v_mul_f32_e32 v209, 0xbfb8aa3b, v209
	v_exp_f32_e32 v206, v206
	v_exp_f32_e32 v207, v207
	v_exp_f32_e32 v208, v208
	v_exp_f32_e32 v209, v209
	s_nop 0
	v_add_f32_e32 v206, 1.0, v206
	v_add_f32_e32 v207, 1.0, v207
	v_add_f32_e32 v208, 1.0, v208
	v_add_f32_e32 v209, 1.0, v209
	v_rcp_f32_e32 v206, v206
	v_rcp_f32_e32 v207, v207
	v_rcp_f32_e32 v208, v208
	v_rcp_f32_e32 v209, v209
	s_nop 0
	v_pk_mul_f32 v[96:97], v[96:97], v[206:207]
	v_pk_mul_f32 v[98:99], v[98:99], v[208:209]
	global_load_dwordx2 v[178:179], v[200:201], off offset:288
	s_waitcnt vmcnt(15)
	v_lshlrev_b32_e32 v206, 16, v180
	v_and_b32_e32 v207, 0xffff0000, v180
	v_lshlrev_b32_e32 v208, 16, v181
	v_and_b32_e32 v209, 0xffff0000, v181
	v_mul_f32_e32 v206, 0xbfb8aa3b, v206
	v_mul_f32_e32 v207, 0xbfb8aa3b, v207
	v_mul_f32_e32 v208, 0xbfb8aa3b, v208
	v_mul_f32_e32 v209, 0xbfb8aa3b, v209
	v_exp_f32_e32 v206, v206
	v_exp_f32_e32 v207, v207
	v_exp_f32_e32 v208, v208
	v_exp_f32_e32 v209, v209
	s_nop 0
	v_add_f32_e32 v206, 1.0, v206
	v_add_f32_e32 v207, 1.0, v207
	v_add_f32_e32 v208, 1.0, v208
	v_add_f32_e32 v209, 1.0, v209
	v_rcp_f32_e32 v206, v206
	v_rcp_f32_e32 v207, v207
	v_rcp_f32_e32 v208, v208
	v_rcp_f32_e32 v209, v209
	s_nop 0
	v_pk_mul_f32 v[92:93], v[92:93], v[206:207]
	v_pk_mul_f32 v[94:95], v[94:95], v[208:209]
	s_mov_b64 s[100:101], 0x3c000
	v_lshl_add_u64 v[200:201], v[200:201], 0, s[100:101]
	global_load_dwordx2 v[180:181], v[200:201], off
	s_waitcnt vmcnt(15)
	v_lshlrev_b32_e32 v206, 16, v182
	v_and_b32_e32 v207, 0xffff0000, v182
	v_lshlrev_b32_e32 v208, 16, v183
	v_and_b32_e32 v209, 0xffff0000, v183
	v_mul_f32_e32 v206, 0xbfb8aa3b, v206
	v_mul_f32_e32 v207, 0xbfb8aa3b, v207
	v_mul_f32_e32 v208, 0xbfb8aa3b, v208
	v_mul_f32_e32 v209, 0xbfb8aa3b, v209
	v_exp_f32_e32 v206, v206
	v_exp_f32_e32 v207, v207
	v_exp_f32_e32 v208, v208
	v_exp_f32_e32 v209, v209
	s_nop 0
	v_add_f32_e32 v206, 1.0, v206
	v_add_f32_e32 v207, 1.0, v207
	v_add_f32_e32 v208, 1.0, v208
	v_add_f32_e32 v209, 1.0, v209
	v_rcp_f32_e32 v206, v206
	v_rcp_f32_e32 v207, v207
	v_rcp_f32_e32 v208, v208
	v_rcp_f32_e32 v209, v209
	s_nop 0
	v_pk_mul_f32 v[88:89], v[88:89], v[206:207]
	v_pk_mul_f32 v[90:91], v[90:91], v[208:209]
	global_load_dwordx2 v[182:183], v[200:201], off offset:32
	s_waitcnt vmcnt(15)
	v_lshlrev_b32_e32 v206, 16, v184
	v_and_b32_e32 v207, 0xffff0000, v184
	v_lshlrev_b32_e32 v208, 16, v185
	v_and_b32_e32 v209, 0xffff0000, v185
	v_mul_f32_e32 v206, 0xbfb8aa3b, v206
	v_mul_f32_e32 v207, 0xbfb8aa3b, v207
	v_mul_f32_e32 v208, 0xbfb8aa3b, v208
	v_mul_f32_e32 v209, 0xbfb8aa3b, v209
	v_exp_f32_e32 v206, v206
	v_exp_f32_e32 v207, v207
	v_exp_f32_e32 v208, v208
	v_exp_f32_e32 v209, v209
	s_nop 0
	v_add_f32_e32 v206, 1.0, v206
	v_add_f32_e32 v207, 1.0, v207
	v_add_f32_e32 v208, 1.0, v208
	v_add_f32_e32 v209, 1.0, v209
	v_rcp_f32_e32 v206, v206
	v_rcp_f32_e32 v207, v207
	v_rcp_f32_e32 v208, v208
	v_rcp_f32_e32 v209, v209
	s_nop 0
	v_pk_mul_f32 v[84:85], v[84:85], v[206:207]
	v_pk_mul_f32 v[86:87], v[86:87], v[208:209]
	global_load_dwordx2 v[184:185], v[200:201], off offset:256
	s_waitcnt vmcnt(15)
	v_lshlrev_b32_e32 v206, 16, v186
	v_and_b32_e32 v207, 0xffff0000, v186
	v_lshlrev_b32_e32 v208, 16, v187
	v_and_b32_e32 v209, 0xffff0000, v187
	v_mul_f32_e32 v206, 0xbfb8aa3b, v206
	v_mul_f32_e32 v207, 0xbfb8aa3b, v207
	v_mul_f32_e32 v208, 0xbfb8aa3b, v208
	v_mul_f32_e32 v209, 0xbfb8aa3b, v209
	v_exp_f32_e32 v206, v206
	v_exp_f32_e32 v207, v207
	v_exp_f32_e32 v208, v208
	v_exp_f32_e32 v209, v209
	s_nop 0
	v_add_f32_e32 v206, 1.0, v206
	v_add_f32_e32 v207, 1.0, v207
	v_add_f32_e32 v208, 1.0, v208
	v_add_f32_e32 v209, 1.0, v209
	v_rcp_f32_e32 v206, v206
	v_rcp_f32_e32 v207, v207
	v_rcp_f32_e32 v208, v208
	v_rcp_f32_e32 v209, v209
	s_nop 0
	v_pk_mul_f32 v[80:81], v[80:81], v[206:207]
	v_pk_mul_f32 v[82:83], v[82:83], v[208:209]
	global_load_dwordx2 v[186:187], v[200:201], off offset:288
	s_waitcnt vmcnt(15)
	v_lshlrev_b32_e32 v206, 16, v188
	v_and_b32_e32 v207, 0xffff0000, v188
	v_lshlrev_b32_e32 v208, 16, v189
	v_and_b32_e32 v209, 0xffff0000, v189
	v_mul_f32_e32 v206, 0xbfb8aa3b, v206
	v_mul_f32_e32 v207, 0xbfb8aa3b, v207
	v_mul_f32_e32 v208, 0xbfb8aa3b, v208
	v_mul_f32_e32 v209, 0xbfb8aa3b, v209
	v_exp_f32_e32 v206, v206
	v_exp_f32_e32 v207, v207
	v_exp_f32_e32 v208, v208
	v_exp_f32_e32 v209, v209
	s_nop 0
	v_add_f32_e32 v206, 1.0, v206
	v_add_f32_e32 v207, 1.0, v207
	v_add_f32_e32 v208, 1.0, v208
	v_add_f32_e32 v209, 1.0, v209
	v_rcp_f32_e32 v206, v206
	v_rcp_f32_e32 v207, v207
	v_rcp_f32_e32 v208, v208
	v_rcp_f32_e32 v209, v209
	s_nop 0
	v_pk_mul_f32 v[76:77], v[76:77], v[206:207]
	v_pk_mul_f32 v[78:79], v[78:79], v[208:209]
	s_mov_b64 s[100:101], 0x3c000
	v_lshl_add_u64 v[200:201], v[200:201], 0, s[100:101]
	global_load_dwordx2 v[188:189], v[200:201], off
	s_waitcnt vmcnt(15)
	v_lshlrev_b32_e32 v206, 16, v190
	v_and_b32_e32 v207, 0xffff0000, v190
	v_lshlrev_b32_e32 v208, 16, v191
	v_and_b32_e32 v209, 0xffff0000, v191
	v_mul_f32_e32 v206, 0xbfb8aa3b, v206
	v_mul_f32_e32 v207, 0xbfb8aa3b, v207
	v_mul_f32_e32 v208, 0xbfb8aa3b, v208
	v_mul_f32_e32 v209, 0xbfb8aa3b, v209
	v_exp_f32_e32 v206, v206
	v_exp_f32_e32 v207, v207
	v_exp_f32_e32 v208, v208
	v_exp_f32_e32 v209, v209
	s_nop 0
	v_add_f32_e32 v206, 1.0, v206
	v_add_f32_e32 v207, 1.0, v207
	v_add_f32_e32 v208, 1.0, v208
	v_add_f32_e32 v209, 1.0, v209
	v_rcp_f32_e32 v206, v206
	v_rcp_f32_e32 v207, v207
	v_rcp_f32_e32 v208, v208
	v_rcp_f32_e32 v209, v209
	s_nop 0
	v_pk_mul_f32 v[72:73], v[72:73], v[206:207]
	v_pk_mul_f32 v[74:75], v[74:75], v[208:209]
	global_load_dwordx2 v[190:191], v[200:201], off offset:32
	s_waitcnt vmcnt(15)
	v_lshlrev_b32_e32 v206, 16, v192
	v_and_b32_e32 v207, 0xffff0000, v192
	v_lshlrev_b32_e32 v208, 16, v193
	v_and_b32_e32 v209, 0xffff0000, v193
	v_mul_f32_e32 v206, 0xbfb8aa3b, v206
	v_mul_f32_e32 v207, 0xbfb8aa3b, v207
	v_mul_f32_e32 v208, 0xbfb8aa3b, v208
	v_mul_f32_e32 v209, 0xbfb8aa3b, v209
	v_exp_f32_e32 v206, v206
	v_exp_f32_e32 v207, v207
	v_exp_f32_e32 v208, v208
	v_exp_f32_e32 v209, v209
	s_nop 0
	v_add_f32_e32 v206, 1.0, v206
	v_add_f32_e32 v207, 1.0, v207
	v_add_f32_e32 v208, 1.0, v208
	v_add_f32_e32 v209, 1.0, v209
	v_rcp_f32_e32 v206, v206
	v_rcp_f32_e32 v207, v207
	v_rcp_f32_e32 v208, v208
	v_rcp_f32_e32 v209, v209
	s_nop 0
	v_pk_mul_f32 v[68:69], v[68:69], v[206:207]
	v_pk_mul_f32 v[70:71], v[70:71], v[208:209]
	global_load_dwordx2 v[192:193], v[200:201], off offset:256
	s_waitcnt vmcnt(15)
	v_lshlrev_b32_e32 v206, 16, v194
	v_and_b32_e32 v207, 0xffff0000, v194
	v_lshlrev_b32_e32 v208, 16, v195
	v_and_b32_e32 v209, 0xffff0000, v195
	v_mul_f32_e32 v206, 0xbfb8aa3b, v206
	v_mul_f32_e32 v207, 0xbfb8aa3b, v207
	v_mul_f32_e32 v208, 0xbfb8aa3b, v208
	v_mul_f32_e32 v209, 0xbfb8aa3b, v209
	v_exp_f32_e32 v206, v206
	v_exp_f32_e32 v207, v207
	v_exp_f32_e32 v208, v208
	v_exp_f32_e32 v209, v209
	s_nop 0
	v_add_f32_e32 v206, 1.0, v206
	v_add_f32_e32 v207, 1.0, v207
	v_add_f32_e32 v208, 1.0, v208
	v_add_f32_e32 v209, 1.0, v209
	v_rcp_f32_e32 v206, v206
	v_rcp_f32_e32 v207, v207
	v_rcp_f32_e32 v208, v208
	v_rcp_f32_e32 v209, v209
	s_nop 0
	v_pk_mul_f32 v[64:65], v[64:65], v[206:207]
	v_pk_mul_f32 v[66:67], v[66:67], v[208:209]
	global_load_dwordx2 v[194:195], v[200:201], off offset:288
	s_waitcnt vmcnt(15)
	v_lshlrev_b32_e32 v206, 16, v164
	v_and_b32_e32 v207, 0xffff0000, v164
	v_lshlrev_b32_e32 v208, 16, v165
	v_and_b32_e32 v209, 0xffff0000, v165
	v_mul_f32_e32 v206, 0xbfb8aa3b, v206
	v_mul_f32_e32 v207, 0xbfb8aa3b, v207
	v_mul_f32_e32 v208, 0xbfb8aa3b, v208
	v_mul_f32_e32 v209, 0xbfb8aa3b, v209
	v_exp_f32_e32 v206, v206
	v_exp_f32_e32 v207, v207
	v_exp_f32_e32 v208, v208
	v_exp_f32_e32 v209, v209
	s_nop 0
	v_add_f32_e32 v206, 1.0, v206
	v_add_f32_e32 v207, 1.0, v207
	v_add_f32_e32 v208, 1.0, v208
	v_add_f32_e32 v209, 1.0, v209
	v_rcp_f32_e32 v206, v206
	v_rcp_f32_e32 v207, v207
	v_rcp_f32_e32 v208, v208
	v_rcp_f32_e32 v209, v209
	s_nop 0
	v_pk_mul_f32 v[60:61], v[60:61], v[206:207]
	v_pk_mul_f32 v[62:63], v[62:63], v[208:209]
	s_waitcnt vmcnt(14)
	v_lshlrev_b32_e32 v206, 16, v166
	v_and_b32_e32 v207, 0xffff0000, v166
	v_lshlrev_b32_e32 v208, 16, v167
	v_and_b32_e32 v209, 0xffff0000, v167
	v_mul_f32_e32 v206, 0xbfb8aa3b, v206
	v_mul_f32_e32 v207, 0xbfb8aa3b, v207
	v_mul_f32_e32 v208, 0xbfb8aa3b, v208
	v_mul_f32_e32 v209, 0xbfb8aa3b, v209
	v_exp_f32_e32 v206, v206
	v_exp_f32_e32 v207, v207
	v_exp_f32_e32 v208, v208
	v_exp_f32_e32 v209, v209
	s_nop 0
	v_add_f32_e32 v206, 1.0, v206
	v_add_f32_e32 v207, 1.0, v207
	v_add_f32_e32 v208, 1.0, v208
	v_add_f32_e32 v209, 1.0, v209
	v_rcp_f32_e32 v206, v206
	v_rcp_f32_e32 v207, v207
	v_rcp_f32_e32 v208, v208
	v_rcp_f32_e32 v209, v209
	s_nop 0
	v_pk_mul_f32 v[56:57], v[56:57], v[206:207]
	v_pk_mul_f32 v[58:59], v[58:59], v[208:209]
	s_waitcnt vmcnt(13)
	v_lshlrev_b32_e32 v206, 16, v168
	v_and_b32_e32 v207, 0xffff0000, v168
	v_lshlrev_b32_e32 v208, 16, v169
	v_and_b32_e32 v209, 0xffff0000, v169
	v_mul_f32_e32 v206, 0xbfb8aa3b, v206
	v_mul_f32_e32 v207, 0xbfb8aa3b, v207
	v_mul_f32_e32 v208, 0xbfb8aa3b, v208
	v_mul_f32_e32 v209, 0xbfb8aa3b, v209
	v_exp_f32_e32 v206, v206
	v_exp_f32_e32 v207, v207
	v_exp_f32_e32 v208, v208
	v_exp_f32_e32 v209, v209
	s_nop 0
	v_add_f32_e32 v206, 1.0, v206
	v_add_f32_e32 v207, 1.0, v207
	v_add_f32_e32 v208, 1.0, v208
	v_add_f32_e32 v209, 1.0, v209
	v_rcp_f32_e32 v206, v206
	v_rcp_f32_e32 v207, v207
	v_rcp_f32_e32 v208, v208
	v_rcp_f32_e32 v209, v209
	s_nop 0
	v_pk_mul_f32 v[52:53], v[52:53], v[206:207]
	v_pk_mul_f32 v[54:55], v[54:55], v[208:209]
	s_waitcnt vmcnt(12)
	v_lshlrev_b32_e32 v206, 16, v170
	v_and_b32_e32 v207, 0xffff0000, v170
	v_lshlrev_b32_e32 v208, 16, v171
	v_and_b32_e32 v209, 0xffff0000, v171
	v_mul_f32_e32 v206, 0xbfb8aa3b, v206
	v_mul_f32_e32 v207, 0xbfb8aa3b, v207
	v_mul_f32_e32 v208, 0xbfb8aa3b, v208
	v_mul_f32_e32 v209, 0xbfb8aa3b, v209
	v_exp_f32_e32 v206, v206
	v_exp_f32_e32 v207, v207
	v_exp_f32_e32 v208, v208
	v_exp_f32_e32 v209, v209
	s_nop 0
	v_add_f32_e32 v206, 1.0, v206
	v_add_f32_e32 v207, 1.0, v207
	v_add_f32_e32 v208, 1.0, v208
	v_add_f32_e32 v209, 1.0, v209
	v_rcp_f32_e32 v206, v206
	v_rcp_f32_e32 v207, v207
	v_rcp_f32_e32 v208, v208
	v_rcp_f32_e32 v209, v209
	s_nop 0
	v_pk_mul_f32 v[48:49], v[48:49], v[206:207]
	v_pk_mul_f32 v[50:51], v[50:51], v[208:209]
	s_waitcnt vmcnt(11)
	v_lshlrev_b32_e32 v206, 16, v172
	v_and_b32_e32 v207, 0xffff0000, v172
	v_lshlrev_b32_e32 v208, 16, v173
	v_and_b32_e32 v209, 0xffff0000, v173
	v_mul_f32_e32 v206, 0xbfb8aa3b, v206
	v_mul_f32_e32 v207, 0xbfb8aa3b, v207
	v_mul_f32_e32 v208, 0xbfb8aa3b, v208
	v_mul_f32_e32 v209, 0xbfb8aa3b, v209
	v_exp_f32_e32 v206, v206
	v_exp_f32_e32 v207, v207
	v_exp_f32_e32 v208, v208
	v_exp_f32_e32 v209, v209
	s_nop 0
	v_add_f32_e32 v206, 1.0, v206
	v_add_f32_e32 v207, 1.0, v207
	v_add_f32_e32 v208, 1.0, v208
	v_add_f32_e32 v209, 1.0, v209
	v_rcp_f32_e32 v206, v206
	v_rcp_f32_e32 v207, v207
	v_rcp_f32_e32 v208, v208
	v_rcp_f32_e32 v209, v209
	s_nop 0
	v_pk_mul_f32 v[44:45], v[44:45], v[206:207]
	v_pk_mul_f32 v[46:47], v[46:47], v[208:209]
	s_waitcnt vmcnt(10)
	v_lshlrev_b32_e32 v206, 16, v174
	v_and_b32_e32 v207, 0xffff0000, v174
	v_lshlrev_b32_e32 v208, 16, v175
	v_and_b32_e32 v209, 0xffff0000, v175
	v_mul_f32_e32 v206, 0xbfb8aa3b, v206
	v_mul_f32_e32 v207, 0xbfb8aa3b, v207
	v_mul_f32_e32 v208, 0xbfb8aa3b, v208
	v_mul_f32_e32 v209, 0xbfb8aa3b, v209
	v_exp_f32_e32 v206, v206
	v_exp_f32_e32 v207, v207
	v_exp_f32_e32 v208, v208
	v_exp_f32_e32 v209, v209
	s_nop 0
	v_add_f32_e32 v206, 1.0, v206
	v_add_f32_e32 v207, 1.0, v207
	v_add_f32_e32 v208, 1.0, v208
	v_add_f32_e32 v209, 1.0, v209
	v_rcp_f32_e32 v206, v206
	v_rcp_f32_e32 v207, v207
	v_rcp_f32_e32 v208, v208
	v_rcp_f32_e32 v209, v209
	s_nop 0
	v_pk_mul_f32 v[40:41], v[40:41], v[206:207]
	v_pk_mul_f32 v[42:43], v[42:43], v[208:209]
	s_waitcnt vmcnt(9)
	v_lshlrev_b32_e32 v206, 16, v176
	v_and_b32_e32 v207, 0xffff0000, v176
	v_lshlrev_b32_e32 v208, 16, v177
	v_and_b32_e32 v209, 0xffff0000, v177
	v_mul_f32_e32 v206, 0xbfb8aa3b, v206
	v_mul_f32_e32 v207, 0xbfb8aa3b, v207
	v_mul_f32_e32 v208, 0xbfb8aa3b, v208
	v_mul_f32_e32 v209, 0xbfb8aa3b, v209
	v_exp_f32_e32 v206, v206
	v_exp_f32_e32 v207, v207
	v_exp_f32_e32 v208, v208
	v_exp_f32_e32 v209, v209
	s_nop 0
	v_add_f32_e32 v206, 1.0, v206
	v_add_f32_e32 v207, 1.0, v207
	v_add_f32_e32 v208, 1.0, v208
	v_add_f32_e32 v209, 1.0, v209
	v_rcp_f32_e32 v206, v206
	v_rcp_f32_e32 v207, v207
	v_rcp_f32_e32 v208, v208
	v_rcp_f32_e32 v209, v209
	s_nop 0
	v_pk_mul_f32 v[36:37], v[36:37], v[206:207]
	v_pk_mul_f32 v[38:39], v[38:39], v[208:209]
	s_waitcnt vmcnt(8)
	v_lshlrev_b32_e32 v206, 16, v178
	v_and_b32_e32 v207, 0xffff0000, v178
	v_lshlrev_b32_e32 v208, 16, v179
	v_and_b32_e32 v209, 0xffff0000, v179
	v_mul_f32_e32 v206, 0xbfb8aa3b, v206
	v_mul_f32_e32 v207, 0xbfb8aa3b, v207
	v_mul_f32_e32 v208, 0xbfb8aa3b, v208
	v_mul_f32_e32 v209, 0xbfb8aa3b, v209
	v_exp_f32_e32 v206, v206
	v_exp_f32_e32 v207, v207
	v_exp_f32_e32 v208, v208
	v_exp_f32_e32 v209, v209
	s_nop 0
	v_add_f32_e32 v206, 1.0, v206
	v_add_f32_e32 v207, 1.0, v207
	v_add_f32_e32 v208, 1.0, v208
	v_add_f32_e32 v209, 1.0, v209
	v_rcp_f32_e32 v206, v206
	v_rcp_f32_e32 v207, v207
	v_rcp_f32_e32 v208, v208
	v_rcp_f32_e32 v209, v209
	s_nop 0
	v_pk_mul_f32 v[32:33], v[32:33], v[206:207]
	v_pk_mul_f32 v[34:35], v[34:35], v[208:209]
	s_waitcnt vmcnt(7)
	v_lshlrev_b32_e32 v206, 16, v180
	v_and_b32_e32 v207, 0xffff0000, v180
	v_lshlrev_b32_e32 v208, 16, v181
	v_and_b32_e32 v209, 0xffff0000, v181
	v_mul_f32_e32 v206, 0xbfb8aa3b, v206
	v_mul_f32_e32 v207, 0xbfb8aa3b, v207
	v_mul_f32_e32 v208, 0xbfb8aa3b, v208
	v_mul_f32_e32 v209, 0xbfb8aa3b, v209
	v_exp_f32_e32 v206, v206
	v_exp_f32_e32 v207, v207
	v_exp_f32_e32 v208, v208
	v_exp_f32_e32 v209, v209
	s_nop 0
	v_add_f32_e32 v206, 1.0, v206
	v_add_f32_e32 v207, 1.0, v207
	v_add_f32_e32 v208, 1.0, v208
	v_add_f32_e32 v209, 1.0, v209
	v_rcp_f32_e32 v206, v206
	v_rcp_f32_e32 v207, v207
	v_rcp_f32_e32 v208, v208
	v_rcp_f32_e32 v209, v209
	s_nop 0
	v_pk_mul_f32 v[28:29], v[28:29], v[206:207]
	v_pk_mul_f32 v[30:31], v[30:31], v[208:209]
	s_waitcnt vmcnt(6)
	v_lshlrev_b32_e32 v206, 16, v182
	v_and_b32_e32 v207, 0xffff0000, v182
	v_lshlrev_b32_e32 v208, 16, v183
	v_and_b32_e32 v209, 0xffff0000, v183
	v_mul_f32_e32 v206, 0xbfb8aa3b, v206
	v_mul_f32_e32 v207, 0xbfb8aa3b, v207
	v_mul_f32_e32 v208, 0xbfb8aa3b, v208
	v_mul_f32_e32 v209, 0xbfb8aa3b, v209
	v_exp_f32_e32 v206, v206
	v_exp_f32_e32 v207, v207
	v_exp_f32_e32 v208, v208
	v_exp_f32_e32 v209, v209
	s_nop 0
	v_add_f32_e32 v206, 1.0, v206
	v_add_f32_e32 v207, 1.0, v207
	v_add_f32_e32 v208, 1.0, v208
	v_add_f32_e32 v209, 1.0, v209
	v_rcp_f32_e32 v206, v206
	v_rcp_f32_e32 v207, v207
	v_rcp_f32_e32 v208, v208
	v_rcp_f32_e32 v209, v209
	s_nop 0
	v_pk_mul_f32 v[24:25], v[24:25], v[206:207]
	v_pk_mul_f32 v[26:27], v[26:27], v[208:209]
	s_waitcnt vmcnt(5)
	v_lshlrev_b32_e32 v206, 16, v184
	v_and_b32_e32 v207, 0xffff0000, v184
	v_lshlrev_b32_e32 v208, 16, v185
	v_and_b32_e32 v209, 0xffff0000, v185
	v_mul_f32_e32 v206, 0xbfb8aa3b, v206
	v_mul_f32_e32 v207, 0xbfb8aa3b, v207
	v_mul_f32_e32 v208, 0xbfb8aa3b, v208
	v_mul_f32_e32 v209, 0xbfb8aa3b, v209
	v_exp_f32_e32 v206, v206
	v_exp_f32_e32 v207, v207
	v_exp_f32_e32 v208, v208
	v_exp_f32_e32 v209, v209
	s_nop 0
	v_add_f32_e32 v206, 1.0, v206
	v_add_f32_e32 v207, 1.0, v207
	v_add_f32_e32 v208, 1.0, v208
	v_add_f32_e32 v209, 1.0, v209
	v_rcp_f32_e32 v206, v206
	v_rcp_f32_e32 v207, v207
	v_rcp_f32_e32 v208, v208
	v_rcp_f32_e32 v209, v209
	s_nop 0
	v_pk_mul_f32 v[20:21], v[20:21], v[206:207]
	v_pk_mul_f32 v[22:23], v[22:23], v[208:209]
	s_waitcnt vmcnt(4)
	v_lshlrev_b32_e32 v206, 16, v186
	v_and_b32_e32 v207, 0xffff0000, v186
	v_lshlrev_b32_e32 v208, 16, v187
	v_and_b32_e32 v209, 0xffff0000, v187
	v_mul_f32_e32 v206, 0xbfb8aa3b, v206
	v_mul_f32_e32 v207, 0xbfb8aa3b, v207
	v_mul_f32_e32 v208, 0xbfb8aa3b, v208
	v_mul_f32_e32 v209, 0xbfb8aa3b, v209
	v_exp_f32_e32 v206, v206
	v_exp_f32_e32 v207, v207
	v_exp_f32_e32 v208, v208
	v_exp_f32_e32 v209, v209
	s_nop 0
	v_add_f32_e32 v206, 1.0, v206
	v_add_f32_e32 v207, 1.0, v207
	v_add_f32_e32 v208, 1.0, v208
	v_add_f32_e32 v209, 1.0, v209
	v_rcp_f32_e32 v206, v206
	v_rcp_f32_e32 v207, v207
	v_rcp_f32_e32 v208, v208
	v_rcp_f32_e32 v209, v209
	s_nop 0
	v_pk_mul_f32 v[16:17], v[16:17], v[206:207]
	v_pk_mul_f32 v[18:19], v[18:19], v[208:209]
	s_waitcnt vmcnt(3)
	v_lshlrev_b32_e32 v206, 16, v188
	v_and_b32_e32 v207, 0xffff0000, v188
	v_lshlrev_b32_e32 v208, 16, v189
	v_and_b32_e32 v209, 0xffff0000, v189
	v_mul_f32_e32 v206, 0xbfb8aa3b, v206
	v_mul_f32_e32 v207, 0xbfb8aa3b, v207
	v_mul_f32_e32 v208, 0xbfb8aa3b, v208
	v_mul_f32_e32 v209, 0xbfb8aa3b, v209
	v_exp_f32_e32 v206, v206
	v_exp_f32_e32 v207, v207
	v_exp_f32_e32 v208, v208
	v_exp_f32_e32 v209, v209
	s_nop 0
	v_add_f32_e32 v206, 1.0, v206
	v_add_f32_e32 v207, 1.0, v207
	v_add_f32_e32 v208, 1.0, v208
	v_add_f32_e32 v209, 1.0, v209
	v_rcp_f32_e32 v206, v206
	v_rcp_f32_e32 v207, v207
	v_rcp_f32_e32 v208, v208
	v_rcp_f32_e32 v209, v209
	s_nop 0
	v_pk_mul_f32 v[12:13], v[12:13], v[206:207]
	v_pk_mul_f32 v[14:15], v[14:15], v[208:209]
	s_waitcnt vmcnt(2)
	v_lshlrev_b32_e32 v206, 16, v190
	v_and_b32_e32 v207, 0xffff0000, v190
	v_lshlrev_b32_e32 v208, 16, v191
	v_and_b32_e32 v209, 0xffff0000, v191
	v_mul_f32_e32 v206, 0xbfb8aa3b, v206
	v_mul_f32_e32 v207, 0xbfb8aa3b, v207
	v_mul_f32_e32 v208, 0xbfb8aa3b, v208
	v_mul_f32_e32 v209, 0xbfb8aa3b, v209
	v_exp_f32_e32 v206, v206
	v_exp_f32_e32 v207, v207
	v_exp_f32_e32 v208, v208
	v_exp_f32_e32 v209, v209
	s_nop 0
	v_add_f32_e32 v206, 1.0, v206
	v_add_f32_e32 v207, 1.0, v207
	v_add_f32_e32 v208, 1.0, v208
	v_add_f32_e32 v209, 1.0, v209
	v_rcp_f32_e32 v206, v206
	v_rcp_f32_e32 v207, v207
	v_rcp_f32_e32 v208, v208
	v_rcp_f32_e32 v209, v209
	s_nop 0
	v_pk_mul_f32 v[8:9], v[8:9], v[206:207]
	v_pk_mul_f32 v[10:11], v[10:11], v[208:209]
	s_waitcnt vmcnt(1)
	v_lshlrev_b32_e32 v206, 16, v192
	v_and_b32_e32 v207, 0xffff0000, v192
	v_lshlrev_b32_e32 v208, 16, v193
	v_and_b32_e32 v209, 0xffff0000, v193
	v_mul_f32_e32 v206, 0xbfb8aa3b, v206
	v_mul_f32_e32 v207, 0xbfb8aa3b, v207
	v_mul_f32_e32 v208, 0xbfb8aa3b, v208
	v_mul_f32_e32 v209, 0xbfb8aa3b, v209
	v_exp_f32_e32 v206, v206
	v_exp_f32_e32 v207, v207
	v_exp_f32_e32 v208, v208
	v_exp_f32_e32 v209, v209
	s_nop 0
	v_add_f32_e32 v206, 1.0, v206
	v_add_f32_e32 v207, 1.0, v207
	v_add_f32_e32 v208, 1.0, v208
	v_add_f32_e32 v209, 1.0, v209
	v_rcp_f32_e32 v206, v206
	v_rcp_f32_e32 v207, v207
	v_rcp_f32_e32 v208, v208
	v_rcp_f32_e32 v209, v209
	s_nop 0
	v_pk_mul_f32 v[4:5], v[4:5], v[206:207]
	v_pk_mul_f32 v[6:7], v[6:7], v[208:209]
	s_waitcnt vmcnt(0)
	v_lshlrev_b32_e32 v206, 16, v194
	v_and_b32_e32 v207, 0xffff0000, v194
	v_lshlrev_b32_e32 v208, 16, v195
	v_and_b32_e32 v209, 0xffff0000, v195
	v_mul_f32_e32 v206, 0xbfb8aa3b, v206
	v_mul_f32_e32 v207, 0xbfb8aa3b, v207
	v_mul_f32_e32 v208, 0xbfb8aa3b, v208
	v_mul_f32_e32 v209, 0xbfb8aa3b, v209
	v_exp_f32_e32 v206, v206
	v_exp_f32_e32 v207, v207
	v_exp_f32_e32 v208, v208
	v_exp_f32_e32 v209, v209
	s_nop 0
	v_add_f32_e32 v206, 1.0, v206
	v_add_f32_e32 v207, 1.0, v207
	v_add_f32_e32 v208, 1.0, v208
	v_add_f32_e32 v209, 1.0, v209
	v_rcp_f32_e32 v206, v206
	v_rcp_f32_e32 v207, v207
	v_rcp_f32_e32 v208, v208
	v_rcp_f32_e32 v209, v209
	s_nop 0
	v_pk_mul_f32 v[0:1], v[0:1], v[206:207]
	v_pk_mul_f32 v[2:3], v[2:3], v[208:209]
	v_readlane_b32 vcc_hi, v214, 2
	s_and_b32 vcc_hi, vcc_hi, 15
	s_cmp_eq_u32 vcc_hi, 1
	s_cbranch_scc0 .Lepi_p2_bf16
	global_load_dwordx4 v[164:167], v[202:203], off
	global_load_dwordx4 v[168:171], v[202:203], off offset:64
	global_load_dwordx4 v[172:175], v[202:203], off offset:512
	global_load_dwordx4 v[176:179], v[202:203], off offset:576
	s_mov_b64 s[100:101], 0x10000
	v_lshl_add_u64 v[202:203], v[202:203], 0, s[100:101]
	global_load_dwordx4 v[180:183], v[202:203], off
	global_load_dwordx4 v[184:187], v[202:203], off offset:64
	global_load_dwordx4 v[188:191], v[202:203], off offset:512
	global_load_dwordx4 v[192:195], v[202:203], off offset:576
	s_waitcnt vmcnt(7)
	v_pk_add_f32 v[124:125], v[124:125], v[164:165]
	v_pk_add_f32 v[126:127], v[126:127], v[166:167]
	global_store_dwordx4 v[204:205], v[124:127], off
	s_mov_b64 s[100:101], 0x10000
	v_lshl_add_u64 v[202:203], v[202:203], 0, s[100:101]
	global_load_dwordx4 v[164:167], v[202:203], off
	s_waitcnt vmcnt(8)
	v_pk_add_f32 v[120:121], v[120:121], v[168:169]
	v_pk_add_f32 v[122:123], v[122:123], v[170:171]
	global_store_dwordx4 v[204:205], v[120:123], off offset:64
	global_load_dwordx4 v[168:171], v[202:203], off offset:64
	s_waitcnt vmcnt(9)
	v_pk_add_f32 v[116:117], v[116:117], v[172:173]
	v_pk_add_f32 v[118:119], v[118:119], v[174:175]
	global_store_dwordx4 v[204:205], v[116:119], off offset:512
	global_load_dwordx4 v[172:175], v[202:203], off offset:512
	s_waitcnt vmcnt(10)
	v_pk_add_f32 v[112:113], v[112:113], v[176:177]
	v_pk_add_f32 v[114:115], v[114:115], v[178:179]
	global_store_dwordx4 v[204:205], v[112:115], off offset:576
	global_load_dwordx4 v[176:179], v[202:203], off offset:576
	s_waitcnt vmcnt(11)
	v_pk_add_f32 v[108:109], v[108:109], v[180:181]
	v_pk_add_f32 v[110:111], v[110:111], v[182:183]
	s_mov_b64 s[100:101], 0x10000
	v_lshl_add_u64 v[204:205], v[204:205], 0, s[100:101]
	global_store_dwordx4 v[204:205], v[108:111], off
	s_mov_b64 s[100:101], 0x10000
	v_lshl_add_u64 v[202:203], v[202:203], 0, s[100:101]
	global_load_dwordx4 v[180:183], v[202:203], off
	s_waitcnt vmcnt(12)
	v_pk_add_f32 v[104:105], v[104:105], v[184:185]
	v_pk_add_f32 v[106:107], v[106:107], v[186:187]
	global_store_dwordx4 v[204:205], v[104:107], off offset:64
	global_load_dwordx4 v[184:187], v[202:203], off offset:64
	s_waitcnt vmcnt(13)
	v_pk_add_f32 v[100:101], v[100:101], v[188:189]
	v_pk_add_f32 v[102:103], v[102:103], v[190:191]
	global_store_dwordx4 v[204:205], v[100:103], off offset:512
	global_load_dwordx4 v[188:191], v[202:203], off offset:512
	s_waitcnt vmcnt(14)
	v_pk_add_f32 v[96:97], v[96:97], v[192:193]
	v_pk_add_f32 v[98:99], v[98:99], v[194:195]
	global_store_dwordx4 v[204:205], v[96:99], off offset:576
	global_load_dwordx4 v[192:195], v[202:203], off offset:576
	s_waitcnt vmcnt(14)
	v_pk_add_f32 v[92:93], v[92:93], v[164:165]
	v_pk_add_f32 v[94:95], v[94:95], v[166:167]
	s_mov_b64 s[100:101], 0x10000
	v_lshl_add_u64 v[204:205], v[204:205], 0, s[100:101]
	global_store_dwordx4 v[204:205], v[92:95], off
	s_mov_b64 s[100:101], 0x50000
	v_lshl_add_u64 v[202:203], v[202:203], 0, s[100:101]
	global_load_dwordx4 v[164:167], v[202:203], off
	s_waitcnt vmcnt(14)
	v_pk_add_f32 v[88:89], v[88:89], v[168:169]
	v_pk_add_f32 v[90:91], v[90:91], v[170:171]
	global_store_dwordx4 v[204:205], v[88:91], off offset:64
	global_load_dwordx4 v[168:171], v[202:203], off offset:64
	s_waitcnt vmcnt(14)
	v_pk_add_f32 v[84:85], v[84:85], v[172:173]
	v_pk_add_f32 v[86:87], v[86:87], v[174:175]
	global_store_dwordx4 v[204:205], v[84:87], off offset:512
	global_load_dwordx4 v[172:175], v[202:203], off offset:512
	s_waitcnt vmcnt(14)
	v_pk_add_f32 v[80:81], v[80:81], v[176:177]
	v_pk_add_f32 v[82:83], v[82:83], v[178:179]
	global_store_dwordx4 v[204:205], v[80:83], off offset:576
	global_load_dwordx4 v[176:179], v[202:203], off offset:576
	s_waitcnt vmcnt(14)
	v_pk_add_f32 v[76:77], v[76:77], v[180:181]
	v_pk_add_f32 v[78:79], v[78:79], v[182:183]
	s_mov_b64 s[100:101], 0x10000
	v_lshl_add_u64 v[204:205], v[204:205], 0, s[100:101]
	global_store_dwordx4 v[204:205], v[76:79], off
	s_mov_b64 s[100:101], 0x10000
	v_lshl_add_u64 v[202:203], v[202:203], 0, s[100:101]
	global_load_dwordx4 v[180:183], v[202:203], off
	s_waitcnt vmcnt(14)
	v_pk_add_f32 v[72:73], v[72:73], v[184:185]
	v_pk_add_f32 v[74:75], v[74:75], v[186:187]
	global_store_dwordx4 v[204:205], v[72:75], off offset:64
	global_load_dwordx4 v[184:187], v[202:203], off offset:64
	s_waitcnt vmcnt(14)
	v_pk_add_f32 v[68:69], v[68:69], v[188:189]
	v_pk_add_f32 v[70:71], v[70:71], v[190:191]
	global_store_dwordx4 v[204:205], v[68:71], off offset:512
	global_load_dwordx4 v[188:191], v[202:203], off offset:512
	s_waitcnt vmcnt(14)
	v_pk_add_f32 v[64:65], v[64:65], v[192:193]
	v_pk_add_f32 v[66:67], v[66:67], v[194:195]
	global_store_dwordx4 v[204:205], v[64:67], off offset:576
	global_load_dwordx4 v[192:195], v[202:203], off offset:576
	s_waitcnt vmcnt(14)
	v_pk_add_f32 v[60:61], v[60:61], v[164:165]
	v_pk_add_f32 v[62:63], v[62:63], v[166:167]
	s_mov_b64 s[100:101], 0x50000
	v_lshl_add_u64 v[204:205], v[204:205], 0, s[100:101]
	global_store_dwordx4 v[204:205], v[60:63], off
	s_mov_b64 s[100:101], 0x10000
	v_lshl_add_u64 v[202:203], v[202:203], 0, s[100:101]
	global_load_dwordx4 v[164:167], v[202:203], off
	s_waitcnt vmcnt(14)
	v_pk_add_f32 v[56:57], v[56:57], v[168:169]
	v_pk_add_f32 v[58:59], v[58:59], v[170:171]
	global_store_dwordx4 v[204:205], v[56:59], off offset:64
	global_load_dwordx4 v[168:171], v[202:203], off offset:64
	s_waitcnt vmcnt(14)
	v_pk_add_f32 v[52:53], v[52:53], v[172:173]
	v_pk_add_f32 v[54:55], v[54:55], v[174:175]
	global_store_dwordx4 v[204:205], v[52:55], off offset:512
	global_load_dwordx4 v[172:175], v[202:203], off offset:512
	s_waitcnt vmcnt(14)
	v_pk_add_f32 v[48:49], v[48:49], v[176:177]
	v_pk_add_f32 v[50:51], v[50:51], v[178:179]
	global_store_dwordx4 v[204:205], v[48:51], off offset:576
	global_load_dwordx4 v[176:179], v[202:203], off offset:576
	s_waitcnt vmcnt(14)
	v_pk_add_f32 v[44:45], v[44:45], v[180:181]
	v_pk_add_f32 v[46:47], v[46:47], v[182:183]
	s_mov_b64 s[100:101], 0x10000
	v_lshl_add_u64 v[204:205], v[204:205], 0, s[100:101]
	global_store_dwordx4 v[204:205], v[44:47], off
	s_mov_b64 s[100:101], 0x10000
	v_lshl_add_u64 v[202:203], v[202:203], 0, s[100:101]
	global_load_dwordx4 v[180:183], v[202:203], off
	s_waitcnt vmcnt(14)
	v_pk_add_f32 v[40:41], v[40:41], v[184:185]
	v_pk_add_f32 v[42:43], v[42:43], v[186:187]
	global_store_dwordx4 v[204:205], v[40:43], off offset:64
	global_load_dwordx4 v[184:187], v[202:203], off offset:64
	s_waitcnt vmcnt(14)
	v_pk_add_f32 v[36:37], v[36:37], v[188:189]
	v_pk_add_f32 v[38:39], v[38:39], v[190:191]
	global_store_dwordx4 v[204:205], v[36:39], off offset:512
	global_load_dwordx4 v[188:191], v[202:203], off offset:512
	s_waitcnt vmcnt(14)
	v_pk_add_f32 v[32:33], v[32:33], v[192:193]
	v_pk_add_f32 v[34:35], v[34:35], v[194:195]
	global_store_dwordx4 v[204:205], v[32:35], off offset:576
	global_load_dwordx4 v[192:195], v[202:203], off offset:576
	s_waitcnt vmcnt(14)
	v_pk_add_f32 v[28:29], v[28:29], v[164:165]
	v_pk_add_f32 v[30:31], v[30:31], v[166:167]
	s_mov_b64 s[100:101], 0x10000
	v_lshl_add_u64 v[204:205], v[204:205], 0, s[100:101]
	global_store_dwordx4 v[204:205], v[28:31], off
	s_waitcnt vmcnt(13)
	v_pk_add_f32 v[24:25], v[24:25], v[168:169]
	v_pk_add_f32 v[26:27], v[26:27], v[170:171]
	global_store_dwordx4 v[204:205], v[24:27], off offset:64
	s_waitcnt vmcnt(12)
	v_pk_add_f32 v[20:21], v[20:21], v[172:173]
	v_pk_add_f32 v[22:23], v[22:23], v[174:175]
	global_store_dwordx4 v[204:205], v[20:23], off offset:512
	s_waitcnt vmcnt(11)
	v_pk_add_f32 v[16:17], v[16:17], v[176:177]
	v_pk_add_f32 v[18:19], v[18:19], v[178:179]
	global_store_dwordx4 v[204:205], v[16:19], off offset:576
	s_waitcnt vmcnt(10)
	v_pk_add_f32 v[12:13], v[12:13], v[180:181]
	v_pk_add_f32 v[14:15], v[14:15], v[182:183]
	s_mov_b64 s[100:101], 0x10000
	v_lshl_add_u64 v[204:205], v[204:205], 0, s[100:101]
	global_store_dwordx4 v[204:205], v[12:15], off
	s_waitcnt vmcnt(9)
	v_pk_add_f32 v[8:9], v[8:9], v[184:185]
	v_pk_add_f32 v[10:11], v[10:11], v[186:187]
	global_store_dwordx4 v[204:205], v[8:11], off offset:64
	s_waitcnt vmcnt(8)
	v_pk_add_f32 v[4:5], v[4:5], v[188:189]
	v_pk_add_f32 v[6:7], v[6:7], v[190:191]
	global_store_dwordx4 v[204:205], v[4:7], off offset:512
	s_waitcnt vmcnt(7)
	v_pk_add_f32 v[0:1], v[0:1], v[192:193]
	v_pk_add_f32 v[2:3], v[2:3], v[194:195]
	global_store_dwordx4 v[204:205], v[0:3], off offset:576
	s_branch .Lepi_done
.Lepi_p2_bf16:
	global_load_dwordx4 v[164:167], v[202:203], off
	global_load_dwordx4 v[168:171], v[202:203], off offset:64
	global_load_dwordx4 v[172:175], v[202:203], off offset:512
	global_load_dwordx4 v[176:179], v[202:203], off offset:576
	s_mov_b64 s[100:101], 0x10000
	v_lshl_add_u64 v[202:203], v[202:203], 0, s[100:101]
	global_load_dwordx4 v[180:183], v[202:203], off
	global_load_dwordx4 v[184:187], v[202:203], off offset:64
	global_load_dwordx4 v[188:191], v[202:203], off offset:512
	global_load_dwordx4 v[192:195], v[202:203], off offset:576
	s_waitcnt vmcnt(7)
	v_pk_add_f32 v[124:125], v[124:125], v[164:165]
	v_pk_add_f32 v[126:127], v[126:127], v[166:167]
	v_cvt_pk_bf16_f32 v210, v124, v125
	v_cvt_pk_bf16_f32 v211, v126, v127
	global_store_dwordx2 v[204:205], v[210:211], off
	s_mov_b64 s[100:101], 0x10000
	v_lshl_add_u64 v[202:203], v[202:203], 0, s[100:101]
	global_load_dwordx4 v[164:167], v[202:203], off
	s_waitcnt vmcnt(8)
	v_pk_add_f32 v[120:121], v[120:121], v[168:169]
	v_pk_add_f32 v[122:123], v[122:123], v[170:171]
	v_cvt_pk_bf16_f32 v210, v120, v121
	v_cvt_pk_bf16_f32 v211, v122, v123
	global_store_dwordx2 v[204:205], v[210:211], off offset:32
	global_load_dwordx4 v[168:171], v[202:203], off offset:64
	s_waitcnt vmcnt(9)
	v_pk_add_f32 v[116:117], v[116:117], v[172:173]
	v_pk_add_f32 v[118:119], v[118:119], v[174:175]
	v_cvt_pk_bf16_f32 v210, v116, v117
	v_cvt_pk_bf16_f32 v211, v118, v119
	global_store_dwordx2 v[204:205], v[210:211], off offset:256
	global_load_dwordx4 v[172:175], v[202:203], off offset:512
	s_waitcnt vmcnt(10)
	v_pk_add_f32 v[112:113], v[112:113], v[176:177]
	v_pk_add_f32 v[114:115], v[114:115], v[178:179]
	v_cvt_pk_bf16_f32 v210, v112, v113
	v_cvt_pk_bf16_f32 v211, v114, v115
	global_store_dwordx2 v[204:205], v[210:211], off offset:288
	global_load_dwordx4 v[176:179], v[202:203], off offset:576
	s_waitcnt vmcnt(11)
	v_pk_add_f32 v[108:109], v[108:109], v[180:181]
	v_pk_add_f32 v[110:111], v[110:111], v[182:183]
	s_mov_b64 s[100:101], 0x8000
	v_lshl_add_u64 v[204:205], v[204:205], 0, s[100:101]
	v_cvt_pk_bf16_f32 v210, v108, v109
	v_cvt_pk_bf16_f32 v211, v110, v111
	global_store_dwordx2 v[204:205], v[210:211], off
	s_mov_b64 s[100:101], 0x10000
	v_lshl_add_u64 v[202:203], v[202:203], 0, s[100:101]
	global_load_dwordx4 v[180:183], v[202:203], off
	s_waitcnt vmcnt(12)
	v_pk_add_f32 v[104:105], v[104:105], v[184:185]
	v_pk_add_f32 v[106:107], v[106:107], v[186:187]
	v_cvt_pk_bf16_f32 v210, v104, v105
	v_cvt_pk_bf16_f32 v211, v106, v107
	global_store_dwordx2 v[204:205], v[210:211], off offset:32
	global_load_dwordx4 v[184:187], v[202:203], off offset:64
	s_waitcnt vmcnt(13)
	v_pk_add_f32 v[100:101], v[100:101], v[188:189]
	v_pk_add_f32 v[102:103], v[102:103], v[190:191]
	v_cvt_pk_bf16_f32 v210, v100, v101
	v_cvt_pk_bf16_f32 v211, v102, v103
	global_store_dwordx2 v[204:205], v[210:211], off offset:256
	global_load_dwordx4 v[188:191], v[202:203], off offset:512
	s_waitcnt vmcnt(14)
	v_pk_add_f32 v[96:97], v[96:97], v[192:193]
	v_pk_add_f32 v[98:99], v[98:99], v[194:195]
	v_cvt_pk_bf16_f32 v210, v96, v97
	v_cvt_pk_bf16_f32 v211, v98, v99
	global_store_dwordx2 v[204:205], v[210:211], off offset:288
	global_load_dwordx4 v[192:195], v[202:203], off offset:576
	s_waitcnt vmcnt(14)
	v_pk_add_f32 v[92:93], v[92:93], v[164:165]
	v_pk_add_f32 v[94:95], v[94:95], v[166:167]
	s_mov_b64 s[100:101], 0x8000
	v_lshl_add_u64 v[204:205], v[204:205], 0, s[100:101]
	v_cvt_pk_bf16_f32 v210, v92, v93
	v_cvt_pk_bf16_f32 v211, v94, v95
	global_store_dwordx2 v[204:205], v[210:211], off
	s_mov_b64 s[100:101], 0x50000
	v_lshl_add_u64 v[202:203], v[202:203], 0, s[100:101]
	global_load_dwordx4 v[164:167], v[202:203], off
	s_waitcnt vmcnt(14)
	v_pk_add_f32 v[88:89], v[88:89], v[168:169]
	v_pk_add_f32 v[90:91], v[90:91], v[170:171]
	v_cvt_pk_bf16_f32 v210, v88, v89
	v_cvt_pk_bf16_f32 v211, v90, v91
	global_store_dwordx2 v[204:205], v[210:211], off offset:32
	global_load_dwordx4 v[168:171], v[202:203], off offset:64
	s_waitcnt vmcnt(14)
	v_pk_add_f32 v[84:85], v[84:85], v[172:173]
	v_pk_add_f32 v[86:87], v[86:87], v[174:175]
	v_cvt_pk_bf16_f32 v210, v84, v85
	v_cvt_pk_bf16_f32 v211, v86, v87
	global_store_dwordx2 v[204:205], v[210:211], off offset:256
	global_load_dwordx4 v[172:175], v[202:203], off offset:512
	s_waitcnt vmcnt(14)
	v_pk_add_f32 v[80:81], v[80:81], v[176:177]
	v_pk_add_f32 v[82:83], v[82:83], v[178:179]
	v_cvt_pk_bf16_f32 v210, v80, v81
	v_cvt_pk_bf16_f32 v211, v82, v83
	global_store_dwordx2 v[204:205], v[210:211], off offset:288
	global_load_dwordx4 v[176:179], v[202:203], off offset:576
	s_waitcnt vmcnt(14)
	v_pk_add_f32 v[76:77], v[76:77], v[180:181]
	v_pk_add_f32 v[78:79], v[78:79], v[182:183]
	s_mov_b64 s[100:101], 0x8000
	v_lshl_add_u64 v[204:205], v[204:205], 0, s[100:101]
	v_cvt_pk_bf16_f32 v210, v76, v77
	v_cvt_pk_bf16_f32 v211, v78, v79
	global_store_dwordx2 v[204:205], v[210:211], off
	s_mov_b64 s[100:101], 0x10000
	v_lshl_add_u64 v[202:203], v[202:203], 0, s[100:101]
	global_load_dwordx4 v[180:183], v[202:203], off
	s_waitcnt vmcnt(14)
	v_pk_add_f32 v[72:73], v[72:73], v[184:185]
	v_pk_add_f32 v[74:75], v[74:75], v[186:187]
	v_cvt_pk_bf16_f32 v210, v72, v73
	v_cvt_pk_bf16_f32 v211, v74, v75
	global_store_dwordx2 v[204:205], v[210:211], off offset:32
	global_load_dwordx4 v[184:187], v[202:203], off offset:64
	s_waitcnt vmcnt(14)
	v_pk_add_f32 v[68:69], v[68:69], v[188:189]
	v_pk_add_f32 v[70:71], v[70:71], v[190:191]
	v_cvt_pk_bf16_f32 v210, v68, v69
	v_cvt_pk_bf16_f32 v211, v70, v71
	global_store_dwordx2 v[204:205], v[210:211], off offset:256
	global_load_dwordx4 v[188:191], v[202:203], off offset:512
	s_waitcnt vmcnt(14)
	v_pk_add_f32 v[64:65], v[64:65], v[192:193]
	v_pk_add_f32 v[66:67], v[66:67], v[194:195]
	v_cvt_pk_bf16_f32 v210, v64, v65
	v_cvt_pk_bf16_f32 v211, v66, v67
	global_store_dwordx2 v[204:205], v[210:211], off offset:288
	global_load_dwordx4 v[192:195], v[202:203], off offset:576
	s_waitcnt vmcnt(14)
	v_pk_add_f32 v[60:61], v[60:61], v[164:165]
	v_pk_add_f32 v[62:63], v[62:63], v[166:167]
	s_mov_b64 s[100:101], 0x28000
	v_lshl_add_u64 v[204:205], v[204:205], 0, s[100:101]
	v_cvt_pk_bf16_f32 v210, v60, v61
	v_cvt_pk_bf16_f32 v211, v62, v63
	global_store_dwordx2 v[204:205], v[210:211], off
	s_mov_b64 s[100:101], 0x10000
	v_lshl_add_u64 v[202:203], v[202:203], 0, s[100:101]
	global_load_dwordx4 v[164:167], v[202:203], off
	s_waitcnt vmcnt(14)
	v_pk_add_f32 v[56:57], v[56:57], v[168:169]
	v_pk_add_f32 v[58:59], v[58:59], v[170:171]
	v_cvt_pk_bf16_f32 v210, v56, v57
	v_cvt_pk_bf16_f32 v211, v58, v59
	global_store_dwordx2 v[204:205], v[210:211], off offset:32
	global_load_dwordx4 v[168:171], v[202:203], off offset:64
	s_waitcnt vmcnt(14)
	v_pk_add_f32 v[52:53], v[52:53], v[172:173]
	v_pk_add_f32 v[54:55], v[54:55], v[174:175]
	v_cvt_pk_bf16_f32 v210, v52, v53
	v_cvt_pk_bf16_f32 v211, v54, v55
	global_store_dwordx2 v[204:205], v[210:211], off offset:256
	global_load_dwordx4 v[172:175], v[202:203], off offset:512
	s_waitcnt vmcnt(14)
	v_pk_add_f32 v[48:49], v[48:49], v[176:177]
	v_pk_add_f32 v[50:51], v[50:51], v[178:179]
	v_cvt_pk_bf16_f32 v210, v48, v49
	v_cvt_pk_bf16_f32 v211, v50, v51
	global_store_dwordx2 v[204:205], v[210:211], off offset:288
	global_load_dwordx4 v[176:179], v[202:203], off offset:576
	s_waitcnt vmcnt(14)
	v_pk_add_f32 v[44:45], v[44:45], v[180:181]
	v_pk_add_f32 v[46:47], v[46:47], v[182:183]
	s_mov_b64 s[100:101], 0x8000
	v_lshl_add_u64 v[204:205], v[204:205], 0, s[100:101]
	v_cvt_pk_bf16_f32 v210, v44, v45
	v_cvt_pk_bf16_f32 v211, v46, v47
	global_store_dwordx2 v[204:205], v[210:211], off
	s_mov_b64 s[100:101], 0x10000
	v_lshl_add_u64 v[202:203], v[202:203], 0, s[100:101]
	global_load_dwordx4 v[180:183], v[202:203], off
	s_waitcnt vmcnt(14)
	v_pk_add_f32 v[40:41], v[40:41], v[184:185]
	v_pk_add_f32 v[42:43], v[42:43], v[186:187]
	v_cvt_pk_bf16_f32 v210, v40, v41
	v_cvt_pk_bf16_f32 v211, v42, v43
	global_store_dwordx2 v[204:205], v[210:211], off offset:32
	global_load_dwordx4 v[184:187], v[202:203], off offset:64
	s_waitcnt vmcnt(14)
	v_pk_add_f32 v[36:37], v[36:37], v[188:189]
	v_pk_add_f32 v[38:39], v[38:39], v[190:191]
	v_cvt_pk_bf16_f32 v210, v36, v37
	v_cvt_pk_bf16_f32 v211, v38, v39
	global_store_dwordx2 v[204:205], v[210:211], off offset:256
	global_load_dwordx4 v[188:191], v[202:203], off offset:512
	s_waitcnt vmcnt(14)
	v_pk_add_f32 v[32:33], v[32:33], v[192:193]
	v_pk_add_f32 v[34:35], v[34:35], v[194:195]
	v_cvt_pk_bf16_f32 v210, v32, v33
	v_cvt_pk_bf16_f32 v211, v34, v35
	global_store_dwordx2 v[204:205], v[210:211], off offset:288
	global_load_dwordx4 v[192:195], v[202:203], off offset:576
	s_waitcnt vmcnt(14)
	v_pk_add_f32 v[28:29], v[28:29], v[164:165]
	v_pk_add_f32 v[30:31], v[30:31], v[166:167]
	s_mov_b64 s[100:101], 0x8000
	v_lshl_add_u64 v[204:205], v[204:205], 0, s[100:101]
	v_cvt_pk_bf16_f32 v210, v28, v29
	v_cvt_pk_bf16_f32 v211, v30, v31
	global_store_dwordx2 v[204:205], v[210:211], off
	s_waitcnt vmcnt(13)
	v_pk_add_f32 v[24:25], v[24:25], v[168:169]
	v_pk_add_f32 v[26:27], v[26:27], v[170:171]
	v_cvt_pk_bf16_f32 v210, v24, v25
	v_cvt_pk_bf16_f32 v211, v26, v27
	global_store_dwordx2 v[204:205], v[210:211], off offset:32
	s_waitcnt vmcnt(12)
	v_pk_add_f32 v[20:21], v[20:21], v[172:173]
	v_pk_add_f32 v[22:23], v[22:23], v[174:175]
	v_cvt_pk_bf16_f32 v210, v20, v21
	v_cvt_pk_bf16_f32 v211, v22, v23
	global_store_dwordx2 v[204:205], v[210:211], off offset:256
	s_waitcnt vmcnt(11)
	v_pk_add_f32 v[16:17], v[16:17], v[176:177]
	v_pk_add_f32 v[18:19], v[18:19], v[178:179]
	v_cvt_pk_bf16_f32 v210, v16, v17
	v_cvt_pk_bf16_f32 v211, v18, v19
	global_store_dwordx2 v[204:205], v[210:211], off offset:288
	s_waitcnt vmcnt(10)
	v_pk_add_f32 v[12:13], v[12:13], v[180:181]
	v_pk_add_f32 v[14:15], v[14:15], v[182:183]
	s_mov_b64 s[100:101], 0x8000
	v_lshl_add_u64 v[204:205], v[204:205], 0, s[100:101]
	v_cvt_pk_bf16_f32 v210, v12, v13
	v_cvt_pk_bf16_f32 v211, v14, v15
	global_store_dwordx2 v[204:205], v[210:211], off
	s_waitcnt vmcnt(9)
	v_pk_add_f32 v[8:9], v[8:9], v[184:185]
	v_pk_add_f32 v[10:11], v[10:11], v[186:187]
	v_cvt_pk_bf16_f32 v210, v8, v9
	v_cvt_pk_bf16_f32 v211, v10, v11
	global_store_dwordx2 v[204:205], v[210:211], off offset:32
	s_waitcnt vmcnt(8)
	v_pk_add_f32 v[4:5], v[4:5], v[188:189]
	v_pk_add_f32 v[6:7], v[6:7], v[190:191]
	v_cvt_pk_bf16_f32 v210, v4, v5
	v_cvt_pk_bf16_f32 v211, v6, v7
	global_store_dwordx2 v[204:205], v[210:211], off offset:256
	s_waitcnt vmcnt(7)
	v_pk_add_f32 v[0:1], v[0:1], v[192:193]
	v_pk_add_f32 v[2:3], v[2:3], v[194:195]
	v_cvt_pk_bf16_f32 v210, v0, v1
	v_cvt_pk_bf16_f32 v211, v2, v3
	global_store_dwordx2 v[204:205], v[210:211], off offset:288
.Lepi_done:
	v_readlane_b32 s98, v214, 2
	s_lshr_b32 s98, s98, 4
	s_cmp_eq_u32 s98, 0
	s_cbranch_scc1 .Lepi_ret_0
	s_cmp_eq_u32 s98, 1
	s_cbranch_scc1 .Lepi_ret_1
	s_cmp_eq_u32 s98, 2
	s_cbranch_scc1 .Lepi_ret_2
	s_cmp_eq_u32 s98, 3
	s_cbranch_scc1 .Lepi_ret_3
	s_cmp_eq_u32 s98, 4
	s_cbranch_scc1 .Lepi_ret_4
	s_cmp_eq_u32 s98, 5
	s_cbranch_scc1 .Lepi_ret_5
	s_endpgm

.LBB0_943:
	v_writelane_b32 v214, s59, 0
	v_writelane_b32 v214, s60, 1
	s_movk_i32 s98, 0x30
	v_writelane_b32 v214, s98, 2
	s_branch .Lepi_merge
.Lepi_ret_3:
	s_and_b64 vcc, exec, s[4:5]
	s_mov_b64 s[4:5], -1
	s_cbranch_vccnz .LBB0_930
	s_andn2_b64 vcc, exec, s[20:21]
	s_cbranch_vccnz .LBB0_929
	s_barrier
	s_branch .LBB0_929

.LBB0_969:
	v_writelane_b32 v214, s61, 0
	v_writelane_b32 v214, s62, 1
	s_movk_i32 s98, 0x41
	v_writelane_b32 v214, s98, 2
	s_branch .Lepi_merge
.Lepi_ret_4:
	s_and_b64 vcc, exec, s[6:7]
	s_mov_b64 s[6:7], -1
	s_cbranch_vccnz .LBB0_956
	s_andn2_b64 vcc, exec, s[20:21]
	s_cbranch_vccnz .LBB0_955
	s_barrier
	s_branch .LBB0_955

.LBB0_995:
	v_writelane_b32 v214, s63, 0
	v_writelane_b32 v214, s64, 1
	s_movk_i32 s98, 0x52
	v_writelane_b32 v214, s98, 2
	s_branch .Lepi_merge
.Lepi_ret_5:
	s_and_b64 vcc, exec, s[4:5]
	s_mov_b64 s[4:5], -1
	s_cbranch_vccnz .LBB0_982
	s_andn2_b64 vcc, exec, s[8:9]
	s_cbranch_vccnz .LBB0_981
	s_barrier
	s_branch .LBB0_981

	.amdhsa_kernel _Z10fwd_kernel4Args
		.amdhsa_group_segment_fixed_size 0
		.amdhsa_private_segment_fixed_size 0
		.amdhsa_kernarg_size 496
		.amdhsa_user_sgpr_count 2
		.amdhsa_user_sgpr_dispatch_ptr 0
		.amdhsa_user_sgpr_queue_ptr 0
		.amdhsa_user_sgpr_kernarg_segment_ptr 1
		.amdhsa_user_sgpr_dispatch_id 0
		.amdhsa_user_sgpr_kernarg_preload_length 0
		.amdhsa_user_sgpr_kernarg_preload_offset 0
		.amdhsa_user_sgpr_private_segment_size 0
		.amdhsa_uses_dynamic_stack 0
		.amdhsa_enable_private_segment 0
		.amdhsa_system_sgpr_workgroup_id_x 1
		.amdhsa_system_sgpr_workgroup_id_y 0
		.amdhsa_system_sgpr_workgroup_id_z 0
		.amdhsa_system_sgpr_workgroup_info 0
		.amdhsa_system_vgpr_workitem_id 2
		.amdhsa_next_free_vgpr 246
		.amdhsa_next_free_sgpr 102
		.amdhsa_accum_offset 248
		.amdhsa_reserve_vcc 1
		.amdhsa_float_round_mode_32 0
		.amdhsa_float_round_mode_16_64 0
		.amdhsa_float_denorm_mode_32 3
		.amdhsa_float_denorm_mode_16_64 3
		.amdhsa_dx10_clamp 1
		.amdhsa_ieee_mode 1
		.amdhsa_fp16_overflow 0
		.amdhsa_tg_split 0
		.amdhsa_exception_fp_ieee_invalid_op 0
		.amdhsa_exception_fp_denorm_src 0
		.amdhsa_exception_fp_ieee_div_zero 0
		.amdhsa_exception_fp_ieee_overflow 0
		.amdhsa_exception_fp_ieee_underflow 0
		.amdhsa_exception_fp_ieee_inexact 0
		.amdhsa_exception_int_div_zero 0
	.end_amdhsa_kernel

amdhsa.kernels:
  - .agpr_count:     0
    .args:
      - .offset:         0
        .size:           240
        .value_kind:     by_value
      - .offset:         240
        .size:           4
        .value_kind:     hidden_block_count_x
      - .offset:         244
        .size:           4
        .value_kind:     hidden_block_count_y
      - .offset:         248
        .size:           4
        .value_kind:     hidden_block_count_z
      - .offset:         252
        .size:           2
        .value_kind:     hidden_group_size_x
      - .offset:         254
        .size:           2
        .value_kind:     hidden_group_size_y
      - .offset:         256
        .size:           2
        .value_kind:     hidden_group_size_z
      - .offset:         258
        .size:           2
        .value_kind:     hidden_remainder_x
      - .offset:         260
        .size:           2
        .value_kind:     hidden_remainder_y
      - .offset:         262
        .size:           2
        .value_kind:     hidden_remainder_z
      - .offset:         280
        .size:           8
        .value_kind:     hidden_global_offset_x
      - .offset:         288
        .size:           8
        .value_kind:     hidden_global_offset_y
      - .offset:         296
        .size:           8
        .value_kind:     hidden_global_offset_z
      - .offset:         304
        .size:           2
        .value_kind:     hidden_grid_dims
      - .offset:         328
        .size:           8
        .value_kind:     hidden_multigrid_sync_arg
      - .offset:         360
        .size:           4
        .value_kind:     hidden_dynamic_lds_size
    .group_segment_fixed_size: 0
    .kernarg_segment_align: 8
    .kernarg_segment_size: 496
    .language:       OpenCL C
    .language_version:
      - 2
      - 0
    .max_flat_workgroup_size: 512
    .name:           _Z10fwd_kernel4Args
    .private_segment_fixed_size: 0
    .sgpr_count:     108
    .sgpr_spill_count: 621
    .symbol:         _Z10fwd_kernel4Args.kd
    .uniform_work_group_size: 1
    .uses_dynamic_stack: false
    .vgpr_count:     246
    .vgpr_spill_count: 0
    .wavefront_size: 64
